# v77 + K-loops: second K-tile LDS-DMA loads use offset:128 with M0-128 instead of a 64-bit VALU add (4 per 2 K-tiles), M0 wait slots filled with the loop's pointer increments
# baseline (speedup 1.0000x reference)
; #define PG8_STAGE(bufoff, gbase, voff) do { _Pragma("unroll") for (int _i = 0; _i < 2; ++_i) \
;         __builtin_amdgcn_global_load_lds((const unsigned*)((const char*)(gbase) + (voff)[_i]), (PG8_LAS unsigned*)(lds + (bufoff) + ldsw + _i * 8192), 16, 0, 0); } while (0)
; #define PG8_LDA(dst, b, h) do { _Pragma("unroll") for (int m = 0; m < 4; ++m) _Pragma("unroll") for (int k = 0; k < 2; ++k) dst[m][k] = *(const PG8_LAS bf16x8*)(lds + PG8_SA(b, h) + aoff + m * 2048 + k * 1024); } while (0)
; #define PG8_LDB(dst, b, h) do { _Pragma("unroll") for (int n = 0; n < 2; ++n) _Pragma("unroll") for (int k = 0; k < 2; ++k) dst[n][k] = *(const PG8_LAS bf16x8*)(lds + PG8_SB(b, h) + boff + n * 2048 + k * 1024); } while (0)
; #define PG8_MMA(ai, bj, At, Bt) do { __builtin_amdgcn_s_setprio(1); _Pragma("unroll") for (int m = 0; m < 4; ++m) _Pragma("unroll") for (int n = 0; n < 2; ++n) _Pragma("unroll") for (int k = 0; k < 2; ++k) \
;         acc[ai][bj][m][n] = __builtin_amdgcn_mfma_f32_16x16x32_bf16(Bt[n][k], At[m][k], acc[ai][bj][m][n], 0, 0, 0); __builtin_amdgcn_s_setprio(0); } while (0)
; #define PG8_WAIT_V(n) asm volatile("s_waitcnt vmcnt(" #n ")" ::: "memory")
; #define PG8_WAIT_L(n) asm volatile("s_waitcnt lgkmcnt(" #n ")" ::: "memory")
; #define PG8_BAR __builtin_amdgcn_s_barrier()
; #define PG8_SCHED __builtin_amdgcn_sched_barrier(0)
; template <class Epi, class Sched, bool ALIGN_EPI = false, bool SP2 = false>
; __device__ __forceinline__ void gemm_phase(PG8_LAS unsigned char* lds, const Gemm g, const Sched& S, const Epi& E) {
;     ...
;             PG8_LDB(B0, 0, 0); PG8_LDB(B1, 0, 1); PG8_SCHED; PG8_LDA(At, 0, 0); PG8_STAGE(PG8_SA(1, 1), a1 + hstep, voffA);
;             PG8_WAIT_V(8); PG8_WAIT_L(0); PG8_BAR; PG8_MMA(0, 0, At, B0); PG8_MMA(0, 1, At, B1); PG8_BAR; PG8_SCHED;
;             PG8_LDA(At, 0, 1); PG8_STAGE(PG8_SB(0, 0), b2, voffB); PG8_STAGE(PG8_SB(0, 1), b2 + hstep, voffB); PG8_STAGE(PG8_SA(0, 0), a2, voffA);
;             PG8_WAIT_V(8); PG8_WAIT_L(0); PG8_BAR; PG8_MMA(1, 0, At, B0); PG8_MMA(1, 1, At, B1); PG8_BAR; PG8_SCHED;
.LBB0_100:
	s_add_u32 s28, s8, 0xfffc0080
	s_addc_u32 s29, s9, -1
	s_add_i32 s53, 0, 0x10000
	s_cmp_eq_u32 s45, 12
	s_cselect_b32 s31, s3, s29
	s_cselect_b32 s30, s7, s28
	s_cselect_b32 s29, s11, s44
	s_cselect_b32 s28, s21, s23
	s_add_i32 s56, 0, 0x14000
	v_add_u32_e32 v144, s53, v204
	v_add_u32_e32 v160, s56, v204
	ds_read_b128 v[132:135], v144
	ds_read_b128 v[136:139], v144 offset:1024
	ds_read_b128 v[140:143], v144 offset:2048
	ds_read_b128 v[144:147], v144 offset:3072
	ds_read_b128 v[148:151], v160
	ds_read_b128 v[152:155], v160 offset:1024
	ds_read_b128 v[156:159], v160 offset:2048
	ds_read_b128 v[160:163], v160 offset:3072
	v_lshl_add_u64 v[194:195], s[8:9], 0, v[178:179]
	s_add_i32 m0, s42, 0xc000
	ds_read_b128 v[164:167], v205
	ds_read_b128 v[182:185], v205 offset:1024
	ds_read_b128 v[186:189], v205 offset:2048
	ds_read_b128 v[190:193], v205 offset:3072
	ds_read_b128 v[208:211], v205 offset:4096
	ds_read_b128 v[212:215], v205 offset:5120
	ds_read_b128 v[216:219], v205 offset:6144
	ds_read_b128 v[220:223], v205 offset:7168
	global_load_lds_dwordx4 v[194:195], off
	s_add_i32 m0, s42, 0xe000
	v_lshl_add_u64 v[194:195], s[8:9], 0, v[180:181]
	global_load_lds_dwordx4 v[194:195], off
	s_waitcnt vmcnt(8) lgkmcnt(0)
	s_barrier
	s_setprio 1
	v_mfma_f32_16x16x32_bf16 v[128:131], v[132:135], v[164:167], v[128:131]
	v_mfma_f32_16x16x32_bf16 v[124:127], v[140:143], v[164:167], v[124:127]
	v_mfma_f32_16x16x32_bf16 v[112:115], v[132:135], v[186:189], v[112:115]
	v_mfma_f32_16x16x32_bf16 v[108:111], v[140:143], v[186:189], v[108:111]
	v_mfma_f32_16x16x32_bf16 v[96:99], v[132:135], v[208:211], v[96:99]
	v_mfma_f32_16x16x32_bf16 v[92:95], v[140:143], v[208:211], v[92:95]
	v_mfma_f32_16x16x32_bf16 v[80:83], v[132:135], v[216:219], v[80:83]
	v_mfma_f32_16x16x32_bf16 v[76:79], v[140:143], v[216:219], v[76:79]
	v_mfma_f32_16x16x32_bf16 v[128:131], v[136:139], v[182:185], v[128:131]
	v_mfma_f32_16x16x32_bf16 v[124:127], v[144:147], v[182:185], v[124:127]
	v_mfma_f32_16x16x32_bf16 v[112:115], v[136:139], v[190:193], v[112:115]
	v_mfma_f32_16x16x32_bf16 v[108:111], v[144:147], v[190:193], v[108:111]
	v_mfma_f32_16x16x32_bf16 v[96:99], v[136:139], v[212:215], v[96:99]
	v_mfma_f32_16x16x32_bf16 v[92:95], v[144:147], v[212:215], v[92:95]
	v_mfma_f32_16x16x32_bf16 v[80:83], v[136:139], v[220:223], v[80:83]
	v_mfma_f32_16x16x32_bf16 v[76:79], v[144:147], v[220:223], v[76:79]
	s_setprio 0
	s_setprio 1
	v_mfma_f32_16x16x32_bf16 v[120:123], v[148:151], v[164:167], v[120:123]
	v_mfma_f32_16x16x32_bf16 v[116:119], v[156:159], v[164:167], v[116:119]
	v_mfma_f32_16x16x32_bf16 v[104:107], v[148:151], v[186:189], v[104:107]
	v_mfma_f32_16x16x32_bf16 v[100:103], v[156:159], v[186:189], v[100:103]
	v_mfma_f32_16x16x32_bf16 v[88:91], v[148:151], v[208:211], v[88:91]
	v_mfma_f32_16x16x32_bf16 v[84:87], v[156:159], v[208:211], v[84:87]
	v_mfma_f32_16x16x32_bf16 v[72:75], v[148:151], v[216:219], v[72:75]
	v_mfma_f32_16x16x32_bf16 v[68:71], v[156:159], v[216:219], v[68:71]
	v_mfma_f32_16x16x32_bf16 v[120:123], v[152:155], v[182:185], v[120:123]
	v_mfma_f32_16x16x32_bf16 v[116:119], v[160:163], v[182:185], v[116:119]
	v_mfma_f32_16x16x32_bf16 v[104:107], v[152:155], v[190:193], v[104:107]
	v_mfma_f32_16x16x32_bf16 v[100:103], v[160:163], v[190:193], v[100:103]
	v_mfma_f32_16x16x32_bf16 v[88:91], v[152:155], v[212:215], v[88:91]
	v_mfma_f32_16x16x32_bf16 v[84:87], v[160:163], v[212:215], v[84:87]
	v_mfma_f32_16x16x32_bf16 v[72:75], v[152:155], v[220:223], v[72:75]
	v_mfma_f32_16x16x32_bf16 v[68:71], v[160:163], v[220:223], v[68:71]
	s_setprio 0
	s_barrier
	s_add_i32 s53, s53, s41
	v_lshl_add_u64 v[194:195], s[28:29], 0, v[168:169]
	s_mov_b32 m0, s53
	ds_read_b128 v[164:167], v205 offset:16384
	ds_read_b128 v[182:185], v205 offset:17408
	ds_read_b128 v[186:189], v205 offset:18432
	ds_read_b128 v[190:193], v205 offset:19456
	ds_read_b128 v[208:211], v205 offset:20480
	ds_read_b128 v[212:215], v205 offset:21504
	ds_read_b128 v[216:219], v205 offset:22528
	ds_read_b128 v[220:223], v205 offset:23552
	global_load_lds_dwordx4 v[194:195], off
	s_add_i32 m0, s53, 0x2000
	s_add_u32 s54, s28, 0x40000
	v_lshl_add_u64 v[202:203], s[28:29], 0, v[172:173]
	s_addc_u32 s55, s29, 0
	s_add_i32 s53, s56, s41
	global_load_lds_dwordx4 v[202:203], off
	v_lshl_add_u64 v[224:225], s[54:55], 0, v[168:169]
	s_mov_b32 m0, s53
	v_lshl_add_u64 v[226:227], s[30:31], 0, v[170:171]
	global_load_lds_dwordx4 v[224:225], off
	s_add_i32 m0, s53, 0x2000
	v_lshl_add_u64 v[224:225], s[54:55], 0, v[172:173]
	global_load_lds_dwordx4 v[224:225], off
	s_mov_b32 m0, s42
	v_lshl_add_u64 v[224:225], s[30:31], 0, v[0:1]
	global_load_lds_dwordx4 v[224:225], off
	s_mov_b32 m0, s43
	s_add_i32 s53, 0, 0x18000
	global_load_lds_dwordx4 v[226:227], off
	s_waitcnt vmcnt(8) lgkmcnt(0)
	s_barrier
; #define PG8_STAGE(bufoff, gbase, voff) do { _Pragma("unroll") for (int _i = 0; _i < 2; ++_i) \
;         __builtin_amdgcn_global_load_lds((const unsigned*)((const char*)(gbase) + (voff)[_i]), (PG8_LAS unsigned*)(lds + (bufoff) + ldsw + _i * 8192), 16, 0, 0); } while (0)
; #define PG8_LDA(dst, b, h) do { _Pragma("unroll") for (int m = 0; m < 4; ++m) _Pragma("unroll") for (int k = 0; k < 2; ++k) dst[m][k] = *(const PG8_LAS bf16x8*)(lds + PG8_SA(b, h) + aoff + m * 2048 + k * 1024); } while (0)
; #define PG8_LDB(dst, b, h) do { _Pragma("unroll") for (int n = 0; n < 2; ++n) _Pragma("unroll") for (int k = 0; k < 2; ++k) dst[n][k] = *(const PG8_LAS bf16x8*)(lds + PG8_SB(b, h) + boff + n * 2048 + k * 1024); } while (0)
; #define PG8_MMA(ai, bj, At, Bt) do { __builtin_amdgcn_s_setprio(1); _Pragma("unroll") for (int m = 0; m < 4; ++m) _Pragma("unroll") for (int n = 0; n < 2; ++n) _Pragma("unroll") for (int k = 0; k < 2; ++k) \
;         acc[ai][bj][m][n] = __builtin_amdgcn_mfma_f32_16x16x32_bf16(Bt[n][k], At[m][k], acc[ai][bj][m][n], 0, 0, 0); __builtin_amdgcn_s_setprio(0); } while (0)
; #define PG8_WAIT_V(n) asm volatile("s_waitcnt vmcnt(" #n ")" ::: "memory")
; #define PG8_WAIT_L(n) asm volatile("s_waitcnt lgkmcnt(" #n ")" ::: "memory")
; #define PG8_BAR __builtin_amdgcn_s_barrier()
; #define PG8_SCHED __builtin_amdgcn_sched_barrier(0)
; template <class Epi, class Sched, bool ALIGN_EPI = false, bool SP2 = false>
; __device__ __forceinline__ void gemm_phase(PG8_LAS unsigned char* lds, const Gemm g, const Sched& S, const Epi& E) {
;     ...
;             PG8_WAIT_V(8); PG8_WAIT_L(0); PG8_BAR; PG8_MMA(1, 0, At, B0); PG8_MMA(1, 1, At, B1); PG8_BAR; PG8_SCHED;
;             PG8_LDB(B0, 1, 0); PG8_LDB(B1, 1, 1); PG8_SCHED; PG8_LDA(At, 1, 0); PG8_STAGE(PG8_SA(0, 1), a2 + hstep, voffA);
;             PG8_WAIT_V(8); PG8_WAIT_L(0); PG8_BAR; PG8_MMA(0, 0, At, B0); PG8_MMA(0, 1, At, B1); PG8_BAR; PG8_SCHED;
	s_setprio 1
	v_mfma_f32_16x16x32_bf16 v[64:67], v[132:135], v[164:167], v[64:67]
	v_mfma_f32_16x16x32_bf16 v[60:63], v[140:143], v[164:167], v[60:63]
	v_mfma_f32_16x16x32_bf16 v[48:51], v[132:135], v[186:189], v[48:51]
	v_mfma_f32_16x16x32_bf16 v[44:47], v[140:143], v[186:189], v[44:47]
	v_mfma_f32_16x16x32_bf16 v[32:35], v[132:135], v[208:211], v[32:35]
	v_mfma_f32_16x16x32_bf16 v[28:31], v[140:143], v[208:211], v[28:31]
	v_mfma_f32_16x16x32_bf16 v[16:19], v[132:135], v[216:219], v[16:19]
	v_mfma_f32_16x16x32_bf16 v[12:15], v[140:143], v[216:219], v[12:15]
	v_mfma_f32_16x16x32_bf16 v[64:67], v[136:139], v[182:185], v[64:67]
	v_mfma_f32_16x16x32_bf16 v[60:63], v[144:147], v[182:185], v[60:63]
	v_mfma_f32_16x16x32_bf16 v[48:51], v[136:139], v[190:193], v[48:51]
	v_mfma_f32_16x16x32_bf16 v[44:47], v[144:147], v[190:193], v[44:47]
	v_mfma_f32_16x16x32_bf16 v[32:35], v[136:139], v[212:215], v[32:35]
	v_mfma_f32_16x16x32_bf16 v[28:31], v[144:147], v[212:215], v[28:31]
	v_mfma_f32_16x16x32_bf16 v[16:19], v[136:139], v[220:223], v[16:19]
	v_mfma_f32_16x16x32_bf16 v[12:15], v[144:147], v[220:223], v[12:15]
	s_setprio 0
	s_setprio 1
	v_mfma_f32_16x16x32_bf16 v[56:59], v[148:151], v[164:167], v[56:59]
	v_mfma_f32_16x16x32_bf16 v[52:55], v[156:159], v[164:167], v[52:55]
	v_mfma_f32_16x16x32_bf16 v[40:43], v[148:151], v[186:189], v[40:43]
	v_mfma_f32_16x16x32_bf16 v[36:39], v[156:159], v[186:189], v[36:39]
	v_mfma_f32_16x16x32_bf16 v[24:27], v[148:151], v[208:211], v[24:27]
	v_mfma_f32_16x16x32_bf16 v[20:23], v[156:159], v[208:211], v[20:23]
	v_mfma_f32_16x16x32_bf16 v[8:11], v[148:151], v[216:219], v[8:11]
	v_mfma_f32_16x16x32_bf16 v[4:7], v[156:159], v[216:219], v[4:7]
	v_mfma_f32_16x16x32_bf16 v[56:59], v[152:155], v[182:185], v[56:59]
	v_mfma_f32_16x16x32_bf16 v[52:55], v[160:163], v[182:185], v[52:55]
	v_mfma_f32_16x16x32_bf16 v[40:43], v[152:155], v[190:193], v[40:43]
	v_mfma_f32_16x16x32_bf16 v[36:39], v[160:163], v[190:193], v[36:39]
	v_mfma_f32_16x16x32_bf16 v[24:27], v[152:155], v[212:215], v[24:27]
	v_mfma_f32_16x16x32_bf16 v[20:23], v[160:163], v[212:215], v[20:23]
	v_mfma_f32_16x16x32_bf16 v[8:11], v[152:155], v[220:223], v[8:11]
	v_mfma_f32_16x16x32_bf16 v[4:7], v[160:163], v[220:223], v[4:7]
	s_setprio 0
	s_barrier
	s_add_i32 s54, 0, 0x1c000
	v_add_u32_e32 v144, s53, v204
	v_add_u32_e32 v160, s54, v204
	ds_read_b128 v[132:135], v144
	ds_read_b128 v[136:139], v144 offset:1024
	ds_read_b128 v[140:143], v144 offset:2048
	ds_read_b128 v[144:147], v144 offset:3072
	ds_read_b128 v[148:151], v160
	ds_read_b128 v[152:155], v160 offset:1024
	ds_read_b128 v[156:159], v160 offset:2048
	ds_read_b128 v[160:163], v160 offset:3072
	s_add_u32 s30, s30, 0x40000
	s_addc_u32 s31, s31, 0
	s_mov_b32 m0, s46
	v_lshl_add_u64 v[228:229], s[30:31], 0, v[0:1]
	ds_read_b128 v[164:167], v205 offset:32768
	ds_read_b128 v[182:185], v205 offset:33792
	ds_read_b128 v[186:189], v205 offset:34816
	ds_read_b128 v[190:193], v205 offset:35840
	ds_read_b128 v[208:211], v205 offset:36864
	ds_read_b128 v[212:215], v205 offset:37888
	ds_read_b128 v[216:219], v205 offset:38912
	ds_read_b128 v[220:223], v205 offset:39936
	global_load_lds_dwordx4 v[228:229], off
	s_mov_b32 m0, s47
	v_lshl_add_u64 v[228:229], s[30:31], 0, v[170:171]
	global_load_lds_dwordx4 v[228:229], off
	s_waitcnt vmcnt(8) lgkmcnt(0)
	s_barrier
	s_setprio 1
	v_mfma_f32_16x16x32_bf16 v[128:131], v[132:135], v[164:167], v[128:131]
	v_mfma_f32_16x16x32_bf16 v[124:127], v[140:143], v[164:167], v[124:127]
	v_mfma_f32_16x16x32_bf16 v[112:115], v[132:135], v[186:189], v[112:115]
	v_mfma_f32_16x16x32_bf16 v[108:111], v[140:143], v[186:189], v[108:111]
	v_mfma_f32_16x16x32_bf16 v[96:99], v[132:135], v[208:211], v[96:99]
	v_mfma_f32_16x16x32_bf16 v[92:95], v[140:143], v[208:211], v[92:95]
	v_mfma_f32_16x16x32_bf16 v[80:83], v[132:135], v[216:219], v[80:83]
	v_mfma_f32_16x16x32_bf16 v[76:79], v[140:143], v[216:219], v[76:79]
	v_mfma_f32_16x16x32_bf16 v[128:131], v[136:139], v[182:185], v[128:131]
	v_mfma_f32_16x16x32_bf16 v[124:127], v[144:147], v[182:185], v[124:127]
	v_mfma_f32_16x16x32_bf16 v[112:115], v[136:139], v[190:193], v[112:115]
	v_mfma_f32_16x16x32_bf16 v[108:111], v[144:147], v[190:193], v[108:111]
	v_mfma_f32_16x16x32_bf16 v[96:99], v[136:139], v[212:215], v[96:99]
	v_mfma_f32_16x16x32_bf16 v[92:95], v[144:147], v[212:215], v[92:95]
	v_mfma_f32_16x16x32_bf16 v[80:83], v[136:139], v[220:223], v[80:83]
	v_mfma_f32_16x16x32_bf16 v[76:79], v[144:147], v[220:223], v[76:79]
	s_setprio 0
	s_setprio 1
	v_mfma_f32_16x16x32_bf16 v[120:123], v[148:151], v[164:167], v[120:123]
	v_mfma_f32_16x16x32_bf16 v[116:119], v[156:159], v[164:167], v[116:119]
	v_mfma_f32_16x16x32_bf16 v[104:107], v[148:151], v[186:189], v[104:107]
	v_mfma_f32_16x16x32_bf16 v[100:103], v[156:159], v[186:189], v[100:103]
	v_mfma_f32_16x16x32_bf16 v[88:91], v[148:151], v[208:211], v[88:91]
	v_mfma_f32_16x16x32_bf16 v[84:87], v[156:159], v[208:211], v[84:87]
	v_mfma_f32_16x16x32_bf16 v[72:75], v[148:151], v[216:219], v[72:75]
	v_mfma_f32_16x16x32_bf16 v[68:71], v[156:159], v[216:219], v[68:71]
	v_mfma_f32_16x16x32_bf16 v[120:123], v[152:155], v[182:185], v[120:123]
	v_mfma_f32_16x16x32_bf16 v[116:119], v[160:163], v[182:185], v[116:119]
	v_mfma_f32_16x16x32_bf16 v[104:107], v[152:155], v[190:193], v[104:107]
	v_mfma_f32_16x16x32_bf16 v[100:103], v[160:163], v[190:193], v[100:103]
	v_mfma_f32_16x16x32_bf16 v[88:91], v[152:155], v[212:215], v[88:91]
	v_mfma_f32_16x16x32_bf16 v[84:87], v[160:163], v[212:215], v[84:87]
	v_mfma_f32_16x16x32_bf16 v[72:75], v[152:155], v[220:223], v[72:75]
	v_mfma_f32_16x16x32_bf16 v[68:71], v[160:163], v[220:223], v[68:71]
	s_setprio 0
	s_barrier
; #define PG8_STAGE(bufoff, gbase, voff) do { _Pragma("unroll") for (int _i = 0; _i < 2; ++_i) \
;         __builtin_amdgcn_global_load_lds((const unsigned*)((const char*)(gbase) + (voff)[_i]), (PG8_LAS unsigned*)(lds + (bufoff) + ldsw + _i * 8192), 16, 0, 0); } while (0)
; #define PG8_LDA(dst, b, h) do { _Pragma("unroll") for (int m = 0; m < 4; ++m) _Pragma("unroll") for (int k = 0; k < 2; ++k) dst[m][k] = *(const PG8_LAS bf16x8*)(lds + PG8_SA(b, h) + aoff + m * 2048 + k * 1024); } while (0)
; #define PG8_MMA(ai, bj, At, Bt) do { __builtin_amdgcn_s_setprio(1); _Pragma("unroll") for (int m = 0; m < 4; ++m) _Pragma("unroll") for (int n = 0; n < 2; ++n) _Pragma("unroll") for (int k = 0; k < 2; ++k) \
;         acc[ai][bj][m][n] = __builtin_amdgcn_mfma_f32_16x16x32_bf16(Bt[n][k], At[m][k], acc[ai][bj][m][n], 0, 0, 0); __builtin_amdgcn_s_setprio(0); } while (0)
; #define PG8_WAIT_V(n) asm volatile("s_waitcnt vmcnt(" #n ")" ::: "memory")
; #define PG8_WAIT_L(n) asm volatile("s_waitcnt lgkmcnt(" #n ")" ::: "memory")
; #define PG8_BAR __builtin_amdgcn_s_barrier()
; #define PG8_SCHED __builtin_amdgcn_sched_barrier(0)
; template <class Epi, class Sched, bool ALIGN_EPI = false, bool SP2 = false>
; __device__ __forceinline__ void gemm_phase(PG8_LAS unsigned char* lds, const Gemm g, const Sched& S, const Epi& E) {
;     ...
;             PG8_LDA(At, 1, 1); PG8_STAGE(PG8_SB(1, 0), b3, voffB); PG8_STAGE(PG8_SB(1, 1), b3 + hstep, voffB); PG8_STAGE(PG8_SA(1, 0), a3, voffA);
;             PG8_WAIT_V(8); PG8_WAIT_L(0); PG8_BAR; PG8_MMA(1, 0, At, B0); PG8_MMA(1, 1, At, B1); PG8_BAR; PG8_SCHED;
	s_add_i32 s30, s53, s41
	s_add_i32 m0, s30, 0xffffff80
	ds_read_b128 v[164:167], v205 offset:49152
	ds_read_b128 v[182:185], v205 offset:50176
	ds_read_b128 v[186:189], v205 offset:51200
	ds_read_b128 v[190:193], v205 offset:52224
	ds_read_b128 v[208:211], v205 offset:53248
	ds_read_b128 v[212:215], v205 offset:54272
	ds_read_b128 v[216:219], v205 offset:55296
	ds_read_b128 v[220:223], v205 offset:56320
	global_load_lds_dwordx4 v[194:195], off offset:128
	s_add_i32 m0, s30, 0x1f80
	s_add_u32 s28, s28, 0x40080
	s_addc_u32 s29, s29, 0
	s_add_i32 s30, s54, s41
	global_load_lds_dwordx4 v[202:203], off offset:128
	s_mov_b32 m0, s30
	v_lshl_add_u64 v[194:195], s[28:29], 0, v[168:169]
	global_load_lds_dwordx4 v[194:195], off
	s_add_i32 m0, s30, 0x2000
	v_lshl_add_u64 v[194:195], s[28:29], 0, v[172:173]
	global_load_lds_dwordx4 v[194:195], off
	s_add_i32 m0, s50, 0xffffff80
	s_add_u32 s8, s8, 0x100
	s_addc_u32 s9, s9, 0
	global_load_lds_dwordx4 v[224:225], off offset:128
	s_add_i32 m0, s51, 0xffffff80
	s_add_u32 s23, s23, 0x100
	s_addc_u32 s44, s44, 0
	global_load_lds_dwordx4 v[226:227], off offset:128
	s_waitcnt vmcnt(8) lgkmcnt(0)
	s_barrier
	s_setprio 1
	v_mfma_f32_16x16x32_bf16 v[64:67], v[132:135], v[164:167], v[64:67]
	v_mfma_f32_16x16x32_bf16 v[60:63], v[140:143], v[164:167], v[60:63]
	v_mfma_f32_16x16x32_bf16 v[48:51], v[132:135], v[186:189], v[48:51]
	v_mfma_f32_16x16x32_bf16 v[44:47], v[140:143], v[186:189], v[44:47]
	v_mfma_f32_16x16x32_bf16 v[32:35], v[132:135], v[208:211], v[32:35]
	v_mfma_f32_16x16x32_bf16 v[28:31], v[140:143], v[208:211], v[28:31]
	v_mfma_f32_16x16x32_bf16 v[16:19], v[132:135], v[216:219], v[16:19]
	v_mfma_f32_16x16x32_bf16 v[12:15], v[140:143], v[216:219], v[12:15]
	v_mfma_f32_16x16x32_bf16 v[64:67], v[136:139], v[182:185], v[64:67]
	v_mfma_f32_16x16x32_bf16 v[60:63], v[144:147], v[182:185], v[60:63]
	v_mfma_f32_16x16x32_bf16 v[48:51], v[136:139], v[190:193], v[48:51]
	v_mfma_f32_16x16x32_bf16 v[44:47], v[144:147], v[190:193], v[44:47]
	v_mfma_f32_16x16x32_bf16 v[32:35], v[136:139], v[212:215], v[32:35]
	v_mfma_f32_16x16x32_bf16 v[28:31], v[144:147], v[212:215], v[28:31]
	v_mfma_f32_16x16x32_bf16 v[16:19], v[136:139], v[220:223], v[16:19]
	v_mfma_f32_16x16x32_bf16 v[12:15], v[144:147], v[220:223], v[12:15]
	s_setprio 0
	s_setprio 1
	v_mfma_f32_16x16x32_bf16 v[56:59], v[148:151], v[164:167], v[56:59]
	v_mfma_f32_16x16x32_bf16 v[52:55], v[156:159], v[164:167], v[52:55]
	v_mfma_f32_16x16x32_bf16 v[40:43], v[148:151], v[186:189], v[40:43]
	v_mfma_f32_16x16x32_bf16 v[36:39], v[156:159], v[186:189], v[36:39]
	v_mfma_f32_16x16x32_bf16 v[24:27], v[148:151], v[208:211], v[24:27]
	v_mfma_f32_16x16x32_bf16 v[20:23], v[156:159], v[208:211], v[20:23]
	v_mfma_f32_16x16x32_bf16 v[8:11], v[148:151], v[216:219], v[8:11]
	v_mfma_f32_16x16x32_bf16 v[4:7], v[156:159], v[216:219], v[4:7]
	v_mfma_f32_16x16x32_bf16 v[56:59], v[152:155], v[182:185], v[56:59]
	v_mfma_f32_16x16x32_bf16 v[52:55], v[160:163], v[182:185], v[52:55]
	v_mfma_f32_16x16x32_bf16 v[40:43], v[152:155], v[190:193], v[40:43]
	v_mfma_f32_16x16x32_bf16 v[36:39], v[160:163], v[190:193], v[36:39]
	v_mfma_f32_16x16x32_bf16 v[24:27], v[152:155], v[212:215], v[24:27]
	v_mfma_f32_16x16x32_bf16 v[20:23], v[160:163], v[212:215], v[20:23]
	v_mfma_f32_16x16x32_bf16 v[8:11], v[152:155], v[220:223], v[8:11]
	v_mfma_f32_16x16x32_bf16 v[4:7], v[160:163], v[220:223], v[4:7]
	s_setprio 0
	s_barrier
	s_add_i32 s45, s45, 2
	s_cmp_gt_u32 s45, 13
	s_cbranch_scc0 .LBB0_100
	s_and_b64 vcc, exec, s[14:15]
	s_cbranch_vccz .LBB0_103
	s_barrier

; #define PG8_STAGE(bufoff, gbase, voff) do { _Pragma("unroll") for (int _i = 0; _i < 2; ++_i) \
;         __builtin_amdgcn_global_load_lds((const unsigned*)((const char*)(gbase) + (voff)[_i]), (PG8_LAS unsigned*)(lds + (bufoff) + ldsw + _i * 8192), 16, 0, 0); } while (0)
; #define PG8_LDA(dst, b, h) do { _Pragma("unroll") for (int m = 0; m < 4; ++m) _Pragma("unroll") for (int k = 0; k < 2; ++k) dst[m][k] = *(const PG8_LAS bf16x8*)(lds + PG8_SA(b, h) + aoff + m * 2048 + k * 1024); } while (0)
; #define PG8_LDB(dst, b, h) do { _Pragma("unroll") for (int n = 0; n < 2; ++n) _Pragma("unroll") for (int k = 0; k < 2; ++k) dst[n][k] = *(const PG8_LAS bf16x8*)(lds + PG8_SB(b, h) + boff + n * 2048 + k * 1024); } while (0)
; #define PG8_MMA(ai, bj, At, Bt) do { __builtin_amdgcn_s_setprio(1); _Pragma("unroll") for (int m = 0; m < 4; ++m) _Pragma("unroll") for (int n = 0; n < 2; ++n) _Pragma("unroll") for (int k = 0; k < 2; ++k) \
;         acc[ai][bj][m][n] = __builtin_amdgcn_mfma_f32_16x16x32_bf16(Bt[n][k], At[m][k], acc[ai][bj][m][n], 0, 0, 0); __builtin_amdgcn_s_setprio(0); } while (0)
; #define PG8_WAIT_V(n) asm volatile("s_waitcnt vmcnt(" #n ")" ::: "memory")
; #define PG8_WAIT_L(n) asm volatile("s_waitcnt lgkmcnt(" #n ")" ::: "memory")
; #define PG8_BAR __builtin_amdgcn_s_barrier()
; #define PG8_SCHED __builtin_amdgcn_sched_barrier(0)
; template <class Epi, class Sched, bool ALIGN_EPI = false, bool SP2 = false>
; __device__ __forceinline__ void gemm_phase(PG8_LAS unsigned char* lds, const Gemm g, const Sched& S, const Epi& E) {
;     ...
;             PG8_LDB(B0, 0, 0); PG8_LDB(B1, 0, 1); PG8_SCHED; PG8_LDA(At, 0, 0); PG8_STAGE(PG8_SA(1, 1), a1 + hstep, voffA);
;             PG8_WAIT_V(8); PG8_WAIT_L(0); PG8_BAR; PG8_MMA(0, 0, At, B0); PG8_MMA(0, 1, At, B1); PG8_BAR; PG8_SCHED;
;             PG8_LDA(At, 0, 1); PG8_STAGE(PG8_SB(0, 0), b2, voffB); PG8_STAGE(PG8_SB(0, 1), b2 + hstep, voffB); PG8_STAGE(PG8_SA(0, 0), a2, voffA);
;             PG8_WAIT_V(8); PG8_WAIT_L(0); PG8_BAR; PG8_MMA(1, 0, At, B0); PG8_MMA(1, 1, At, B1); PG8_BAR; PG8_SCHED;
.LBB0_329:
	s_add_u32 s30, s28, 0xfffc0080
	s_addc_u32 s31, s29, -1
	s_add_i32 s52, 0, 0x10000
	s_cmp_eq_u32 s45, 12
	s_cselect_b32 s35, s3, s31
	s_cselect_b32 s34, s17, s30
	s_cselect_b32 s31, s19, s44
	s_cselect_b32 s30, s25, s27
	s_add_i32 s54, 0, 0x14000
	v_add_u32_e32 v128, s52, v251
	v_add_u32_e32 v156, s54, v251
	ds_read_b128 v[108:111], v128
	ds_read_b128 v[112:115], v128 offset:1024
	ds_read_b128 v[124:127], v128 offset:2048
	ds_read_b128 v[128:131], v128 offset:3072
	ds_read_b128 v[132:135], v156
	ds_read_b128 v[140:143], v156 offset:1024
	ds_read_b128 v[148:151], v156 offset:2048
	ds_read_b128 v[156:159], v156 offset:3072
	v_lshl_add_u64 v[212:213], s[28:29], 0, v[208:209]
	s_add_i32 m0, s42, 0xc000
	ds_read_b128 v[164:167], v253
	ds_read_b128 v[168:171], v253 offset:1024
	ds_read_b128 v[172:175], v253 offset:2048
	ds_read_b128 v[176:179], v253 offset:3072
	ds_read_b128 v[180:183], v253 offset:4096
	ds_read_b128 v[184:187], v253 offset:5120
	ds_read_b128 v[188:191], v253 offset:6144
	ds_read_b128 v[192:195], v253 offset:7168
	global_load_lds_dwordx4 v[212:213], off
	s_add_i32 m0, s42, 0xe000
	v_lshl_add_u64 v[212:213], s[28:29], 0, v[210:211]
	global_load_lds_dwordx4 v[212:213], off
	s_waitcnt vmcnt(8) lgkmcnt(0)
	s_barrier
	s_setprio 1
	v_mfma_f32_16x16x32_bf16 v[160:163], v[108:111], v[164:167], v[160:163]
	v_mfma_f32_16x16x32_bf16 v[152:155], v[124:127], v[164:167], v[152:155]
	v_mfma_f32_16x16x32_bf16 v[120:123], v[108:111], v[172:175], v[120:123]
	v_mfma_f32_16x16x32_bf16 v[116:119], v[124:127], v[172:175], v[116:119]
	v_mfma_f32_16x16x32_bf16 v[96:99], v[108:111], v[180:183], v[96:99]
	v_mfma_f32_16x16x32_bf16 v[92:95], v[124:127], v[180:183], v[92:95]
	v_mfma_f32_16x16x32_bf16 v[80:83], v[108:111], v[188:191], v[80:83]
	v_mfma_f32_16x16x32_bf16 v[76:79], v[124:127], v[188:191], v[76:79]
	v_mfma_f32_16x16x32_bf16 v[160:163], v[112:115], v[168:171], v[160:163]
	v_mfma_f32_16x16x32_bf16 v[152:155], v[128:131], v[168:171], v[152:155]
	v_mfma_f32_16x16x32_bf16 v[120:123], v[112:115], v[176:179], v[120:123]
	v_mfma_f32_16x16x32_bf16 v[116:119], v[128:131], v[176:179], v[116:119]
	v_mfma_f32_16x16x32_bf16 v[96:99], v[112:115], v[184:187], v[96:99]
	v_mfma_f32_16x16x32_bf16 v[92:95], v[128:131], v[184:187], v[92:95]
	v_mfma_f32_16x16x32_bf16 v[80:83], v[112:115], v[192:195], v[80:83]
	v_mfma_f32_16x16x32_bf16 v[76:79], v[128:131], v[192:195], v[76:79]
	s_setprio 0
	s_setprio 1
	v_mfma_f32_16x16x32_bf16 v[144:147], v[132:135], v[164:167], v[144:147]
	v_mfma_f32_16x16x32_bf16 v[136:139], v[148:151], v[164:167], v[136:139]
	v_mfma_f32_16x16x32_bf16 v[104:107], v[132:135], v[172:175], v[104:107]
	v_mfma_f32_16x16x32_bf16 v[100:103], v[148:151], v[172:175], v[100:103]
	v_mfma_f32_16x16x32_bf16 v[88:91], v[132:135], v[180:183], v[88:91]
	v_mfma_f32_16x16x32_bf16 v[84:87], v[148:151], v[180:183], v[84:87]
	v_mfma_f32_16x16x32_bf16 v[72:75], v[132:135], v[188:191], v[72:75]
	v_mfma_f32_16x16x32_bf16 v[68:71], v[148:151], v[188:191], v[68:71]
	v_mfma_f32_16x16x32_bf16 v[144:147], v[140:143], v[168:171], v[144:147]
	v_mfma_f32_16x16x32_bf16 v[136:139], v[156:159], v[168:171], v[136:139]
	v_mfma_f32_16x16x32_bf16 v[104:107], v[140:143], v[176:179], v[104:107]
	v_mfma_f32_16x16x32_bf16 v[100:103], v[156:159], v[176:179], v[100:103]
	v_mfma_f32_16x16x32_bf16 v[88:91], v[140:143], v[184:187], v[88:91]
	v_mfma_f32_16x16x32_bf16 v[84:87], v[156:159], v[184:187], v[84:87]
	v_mfma_f32_16x16x32_bf16 v[72:75], v[140:143], v[192:195], v[72:75]
	v_mfma_f32_16x16x32_bf16 v[68:71], v[156:159], v[192:195], v[68:71]
	s_setprio 0
	s_barrier
	s_add_i32 s52, s52, s41
	v_lshl_add_u64 v[212:213], s[30:31], 0, v[202:203]
	s_mov_b32 m0, s52
	ds_read_b128 v[164:167], v253 offset:16384
	ds_read_b128 v[168:171], v253 offset:17408
	ds_read_b128 v[172:175], v253 offset:18432
	ds_read_b128 v[176:179], v253 offset:19456
	ds_read_b128 v[180:183], v253 offset:20480
	ds_read_b128 v[184:187], v253 offset:21504
	ds_read_b128 v[188:191], v253 offset:22528
	ds_read_b128 v[192:195], v253 offset:23552
	global_load_lds_dwordx4 v[212:213], off
	s_add_i32 m0, s52, 0x2000
	s_add_u32 s52, s30, 0x40000
	v_lshl_add_u64 v[214:215], s[30:31], 0, v[206:207]
	s_addc_u32 s53, s31, 0
	s_add_i32 s54, s54, s41
	global_load_lds_dwordx4 v[214:215], off
	v_lshl_add_u64 v[216:217], s[52:53], 0, v[202:203]
	s_mov_b32 m0, s54
	v_lshl_add_u64 v[218:219], s[34:35], 0, v[204:205]
	global_load_lds_dwordx4 v[216:217], off
	s_add_i32 m0, s54, 0x2000
	v_lshl_add_u64 v[216:217], s[52:53], 0, v[206:207]
	global_load_lds_dwordx4 v[216:217], off
	s_mov_b32 m0, s42
	v_lshl_add_u64 v[216:217], s[34:35], 0, v[0:1]
	global_load_lds_dwordx4 v[216:217], off
	s_mov_b32 m0, s43
	s_add_i32 s52, 0, 0x18000
	global_load_lds_dwordx4 v[218:219], off
	s_waitcnt vmcnt(8) lgkmcnt(0)
	s_barrier
; #define PG8_STAGE(bufoff, gbase, voff) do { _Pragma("unroll") for (int _i = 0; _i < 2; ++_i) \
;         __builtin_amdgcn_global_load_lds((const unsigned*)((const char*)(gbase) + (voff)[_i]), (PG8_LAS unsigned*)(lds + (bufoff) + ldsw + _i * 8192), 16, 0, 0); } while (0)
; #define PG8_LDA(dst, b, h) do { _Pragma("unroll") for (int m = 0; m < 4; ++m) _Pragma("unroll") for (int k = 0; k < 2; ++k) dst[m][k] = *(const PG8_LAS bf16x8*)(lds + PG8_SA(b, h) + aoff + m * 2048 + k * 1024); } while (0)
; #define PG8_LDB(dst, b, h) do { _Pragma("unroll") for (int n = 0; n < 2; ++n) _Pragma("unroll") for (int k = 0; k < 2; ++k) dst[n][k] = *(const PG8_LAS bf16x8*)(lds + PG8_SB(b, h) + boff + n * 2048 + k * 1024); } while (0)
; #define PG8_MMA(ai, bj, At, Bt) do { __builtin_amdgcn_s_setprio(1); _Pragma("unroll") for (int m = 0; m < 4; ++m) _Pragma("unroll") for (int n = 0; n < 2; ++n) _Pragma("unroll") for (int k = 0; k < 2; ++k) \
;         acc[ai][bj][m][n] = __builtin_amdgcn_mfma_f32_16x16x32_bf16(Bt[n][k], At[m][k], acc[ai][bj][m][n], 0, 0, 0); __builtin_amdgcn_s_setprio(0); } while (0)
; #define PG8_WAIT_V(n) asm volatile("s_waitcnt vmcnt(" #n ")" ::: "memory")
; #define PG8_WAIT_L(n) asm volatile("s_waitcnt lgkmcnt(" #n ")" ::: "memory")
; #define PG8_BAR __builtin_amdgcn_s_barrier()
; #define PG8_SCHED __builtin_amdgcn_sched_barrier(0)
; template <class Epi, class Sched, bool ALIGN_EPI = false, bool SP2 = false>
; __device__ __forceinline__ void gemm_phase(PG8_LAS unsigned char* lds, const Gemm g, const Sched& S, const Epi& E) {
;     ...
;             PG8_WAIT_V(8); PG8_WAIT_L(0); PG8_BAR; PG8_MMA(1, 0, At, B0); PG8_MMA(1, 1, At, B1); PG8_BAR; PG8_SCHED;
;             PG8_LDB(B0, 1, 0); PG8_LDB(B1, 1, 1); PG8_SCHED; PG8_LDA(At, 1, 0); PG8_STAGE(PG8_SA(0, 1), a2 + hstep, voffA);
;             PG8_WAIT_V(8); PG8_WAIT_L(0); PG8_BAR; PG8_MMA(0, 0, At, B0); PG8_MMA(0, 1, At, B1); PG8_BAR; PG8_SCHED;
	s_setprio 1
	v_mfma_f32_16x16x32_bf16 v[64:67], v[108:111], v[164:167], v[64:67]
	v_mfma_f32_16x16x32_bf16 v[60:63], v[124:127], v[164:167], v[60:63]
	v_mfma_f32_16x16x32_bf16 v[48:51], v[108:111], v[172:175], v[48:51]
	v_mfma_f32_16x16x32_bf16 v[44:47], v[124:127], v[172:175], v[44:47]
	v_mfma_f32_16x16x32_bf16 v[32:35], v[108:111], v[180:183], v[32:35]
	v_mfma_f32_16x16x32_bf16 v[28:31], v[124:127], v[180:183], v[28:31]
	v_mfma_f32_16x16x32_bf16 v[16:19], v[108:111], v[188:191], v[16:19]
	v_mfma_f32_16x16x32_bf16 v[12:15], v[124:127], v[188:191], v[12:15]
	v_mfma_f32_16x16x32_bf16 v[64:67], v[112:115], v[168:171], v[64:67]
	v_mfma_f32_16x16x32_bf16 v[60:63], v[128:131], v[168:171], v[60:63]
	v_mfma_f32_16x16x32_bf16 v[48:51], v[112:115], v[176:179], v[48:51]
	v_mfma_f32_16x16x32_bf16 v[44:47], v[128:131], v[176:179], v[44:47]
	v_mfma_f32_16x16x32_bf16 v[32:35], v[112:115], v[184:187], v[32:35]
	v_mfma_f32_16x16x32_bf16 v[28:31], v[128:131], v[184:187], v[28:31]
	v_mfma_f32_16x16x32_bf16 v[16:19], v[112:115], v[192:195], v[16:19]
	v_mfma_f32_16x16x32_bf16 v[12:15], v[128:131], v[192:195], v[12:15]
	s_setprio 0
	s_setprio 1
	v_mfma_f32_16x16x32_bf16 v[56:59], v[132:135], v[164:167], v[56:59]
	v_mfma_f32_16x16x32_bf16 v[52:55], v[148:151], v[164:167], v[52:55]
	v_mfma_f32_16x16x32_bf16 v[40:43], v[132:135], v[172:175], v[40:43]
	v_mfma_f32_16x16x32_bf16 v[36:39], v[148:151], v[172:175], v[36:39]
	v_mfma_f32_16x16x32_bf16 v[24:27], v[132:135], v[180:183], v[24:27]
	v_mfma_f32_16x16x32_bf16 v[20:23], v[148:151], v[180:183], v[20:23]
	v_mfma_f32_16x16x32_bf16 v[8:11], v[132:135], v[188:191], v[8:11]
	v_mfma_f32_16x16x32_bf16 v[4:7], v[148:151], v[188:191], v[4:7]
	v_mfma_f32_16x16x32_bf16 v[56:59], v[140:143], v[168:171], v[56:59]
	v_mfma_f32_16x16x32_bf16 v[52:55], v[156:159], v[168:171], v[52:55]
	v_mfma_f32_16x16x32_bf16 v[40:43], v[140:143], v[176:179], v[40:43]
	v_mfma_f32_16x16x32_bf16 v[36:39], v[156:159], v[176:179], v[36:39]
	v_mfma_f32_16x16x32_bf16 v[24:27], v[140:143], v[184:187], v[24:27]
	v_mfma_f32_16x16x32_bf16 v[20:23], v[156:159], v[184:187], v[20:23]
	v_mfma_f32_16x16x32_bf16 v[8:11], v[140:143], v[192:195], v[8:11]
	v_mfma_f32_16x16x32_bf16 v[4:7], v[156:159], v[192:195], v[4:7]
	s_setprio 0
	s_barrier
	s_add_i32 s53, 0, 0x1c000
	v_add_u32_e32 v128, s52, v251
	v_add_u32_e32 v156, s53, v251
	ds_read_b128 v[108:111], v128
	ds_read_b128 v[112:115], v128 offset:1024
	ds_read_b128 v[124:127], v128 offset:2048
	ds_read_b128 v[128:131], v128 offset:3072
	ds_read_b128 v[132:135], v156
	ds_read_b128 v[140:143], v156 offset:1024
	ds_read_b128 v[148:151], v156 offset:2048
	ds_read_b128 v[156:159], v156 offset:3072
	s_add_u32 s34, s34, 0x40000
	s_addc_u32 s35, s35, 0
	s_mov_b32 m0, s46
	v_lshl_add_u64 v[220:221], s[34:35], 0, v[0:1]
	ds_read_b128 v[164:167], v253 offset:32768
	ds_read_b128 v[168:171], v253 offset:33792
	ds_read_b128 v[172:175], v253 offset:34816
	ds_read_b128 v[176:179], v253 offset:35840
	ds_read_b128 v[180:183], v253 offset:36864
	ds_read_b128 v[184:187], v253 offset:37888
	ds_read_b128 v[188:191], v253 offset:38912
	ds_read_b128 v[192:195], v253 offset:39936
	global_load_lds_dwordx4 v[220:221], off
	s_mov_b32 m0, s47
	v_lshl_add_u64 v[220:221], s[34:35], 0, v[204:205]
	global_load_lds_dwordx4 v[220:221], off
	s_waitcnt vmcnt(8) lgkmcnt(0)
	s_barrier
	s_setprio 1
	v_mfma_f32_16x16x32_bf16 v[160:163], v[108:111], v[164:167], v[160:163]
	v_mfma_f32_16x16x32_bf16 v[152:155], v[124:127], v[164:167], v[152:155]
	v_mfma_f32_16x16x32_bf16 v[120:123], v[108:111], v[172:175], v[120:123]
	v_mfma_f32_16x16x32_bf16 v[116:119], v[124:127], v[172:175], v[116:119]
	v_mfma_f32_16x16x32_bf16 v[96:99], v[108:111], v[180:183], v[96:99]
	v_mfma_f32_16x16x32_bf16 v[92:95], v[124:127], v[180:183], v[92:95]
	v_mfma_f32_16x16x32_bf16 v[80:83], v[108:111], v[188:191], v[80:83]
	v_mfma_f32_16x16x32_bf16 v[76:79], v[124:127], v[188:191], v[76:79]
	v_mfma_f32_16x16x32_bf16 v[160:163], v[112:115], v[168:171], v[160:163]
	v_mfma_f32_16x16x32_bf16 v[152:155], v[128:131], v[168:171], v[152:155]
	v_mfma_f32_16x16x32_bf16 v[120:123], v[112:115], v[176:179], v[120:123]
	v_mfma_f32_16x16x32_bf16 v[116:119], v[128:131], v[176:179], v[116:119]
	v_mfma_f32_16x16x32_bf16 v[96:99], v[112:115], v[184:187], v[96:99]
	v_mfma_f32_16x16x32_bf16 v[92:95], v[128:131], v[184:187], v[92:95]
	v_mfma_f32_16x16x32_bf16 v[80:83], v[112:115], v[192:195], v[80:83]
	v_mfma_f32_16x16x32_bf16 v[76:79], v[128:131], v[192:195], v[76:79]
	s_setprio 0
	s_setprio 1
	v_mfma_f32_16x16x32_bf16 v[144:147], v[132:135], v[164:167], v[144:147]
	v_mfma_f32_16x16x32_bf16 v[136:139], v[148:151], v[164:167], v[136:139]
	v_mfma_f32_16x16x32_bf16 v[104:107], v[132:135], v[172:175], v[104:107]
	v_mfma_f32_16x16x32_bf16 v[100:103], v[148:151], v[172:175], v[100:103]
	v_mfma_f32_16x16x32_bf16 v[88:91], v[132:135], v[180:183], v[88:91]
	v_mfma_f32_16x16x32_bf16 v[84:87], v[148:151], v[180:183], v[84:87]
	v_mfma_f32_16x16x32_bf16 v[72:75], v[132:135], v[188:191], v[72:75]
	v_mfma_f32_16x16x32_bf16 v[68:71], v[148:151], v[188:191], v[68:71]
	v_mfma_f32_16x16x32_bf16 v[144:147], v[140:143], v[168:171], v[144:147]
	v_mfma_f32_16x16x32_bf16 v[136:139], v[156:159], v[168:171], v[136:139]
	v_mfma_f32_16x16x32_bf16 v[104:107], v[140:143], v[176:179], v[104:107]
	v_mfma_f32_16x16x32_bf16 v[100:103], v[156:159], v[176:179], v[100:103]
	v_mfma_f32_16x16x32_bf16 v[88:91], v[140:143], v[184:187], v[88:91]
	v_mfma_f32_16x16x32_bf16 v[84:87], v[156:159], v[184:187], v[84:87]
	v_mfma_f32_16x16x32_bf16 v[72:75], v[140:143], v[192:195], v[72:75]
	v_mfma_f32_16x16x32_bf16 v[68:71], v[156:159], v[192:195], v[68:71]
	s_setprio 0
	s_barrier
; #define PG8_STAGE(bufoff, gbase, voff) do { _Pragma("unroll") for (int _i = 0; _i < 2; ++_i) \
;         __builtin_amdgcn_global_load_lds((const unsigned*)((const char*)(gbase) + (voff)[_i]), (PG8_LAS unsigned*)(lds + (bufoff) + ldsw + _i * 8192), 16, 0, 0); } while (0)
; #define PG8_LDA(dst, b, h) do { _Pragma("unroll") for (int m = 0; m < 4; ++m) _Pragma("unroll") for (int k = 0; k < 2; ++k) dst[m][k] = *(const PG8_LAS bf16x8*)(lds + PG8_SA(b, h) + aoff + m * 2048 + k * 1024); } while (0)
; #define PG8_MMA(ai, bj, At, Bt) do { __builtin_amdgcn_s_setprio(1); _Pragma("unroll") for (int m = 0; m < 4; ++m) _Pragma("unroll") for (int n = 0; n < 2; ++n) _Pragma("unroll") for (int k = 0; k < 2; ++k) \
;         acc[ai][bj][m][n] = __builtin_amdgcn_mfma_f32_16x16x32_bf16(Bt[n][k], At[m][k], acc[ai][bj][m][n], 0, 0, 0); __builtin_amdgcn_s_setprio(0); } while (0)
; #define PG8_WAIT_V(n) asm volatile("s_waitcnt vmcnt(" #n ")" ::: "memory")
; #define PG8_WAIT_L(n) asm volatile("s_waitcnt lgkmcnt(" #n ")" ::: "memory")
; #define PG8_BAR __builtin_amdgcn_s_barrier()
; #define PG8_SCHED __builtin_amdgcn_sched_barrier(0)
; template <class Epi, class Sched, bool ALIGN_EPI = false, bool SP2 = false>
; __device__ __forceinline__ void gemm_phase(PG8_LAS unsigned char* lds, const Gemm g, const Sched& S, const Epi& E) {
;     ...
;             PG8_LDA(At, 1, 1); PG8_STAGE(PG8_SB(1, 0), b3, voffB); PG8_STAGE(PG8_SB(1, 1), b3 + hstep, voffB); PG8_STAGE(PG8_SA(1, 0), a3, voffA);
;             PG8_WAIT_V(8); PG8_WAIT_L(0); PG8_BAR; PG8_MMA(1, 0, At, B0); PG8_MMA(1, 1, At, B1); PG8_BAR; PG8_SCHED;
	s_add_i32 s34, s52, s41
	s_add_i32 m0, s34, 0xffffff80
	ds_read_b128 v[164:167], v253 offset:49152
	ds_read_b128 v[168:171], v253 offset:50176
	ds_read_b128 v[172:175], v253 offset:51200
	ds_read_b128 v[176:179], v253 offset:52224
	ds_read_b128 v[180:183], v253 offset:53248
	ds_read_b128 v[184:187], v253 offset:54272
	ds_read_b128 v[188:191], v253 offset:55296
	ds_read_b128 v[192:195], v253 offset:56320
	global_load_lds_dwordx4 v[212:213], off offset:128
	s_add_i32 m0, s34, 0x1f80
	s_add_u32 s30, s30, 0x40080
	s_addc_u32 s31, s31, 0
	s_add_i32 s34, s53, s41
	global_load_lds_dwordx4 v[214:215], off offset:128
	s_mov_b32 m0, s34
	v_lshl_add_u64 v[212:213], s[30:31], 0, v[202:203]
	global_load_lds_dwordx4 v[212:213], off
	s_add_i32 m0, s34, 0x2000
	v_lshl_add_u64 v[212:213], s[30:31], 0, v[206:207]
	global_load_lds_dwordx4 v[212:213], off
	s_add_i32 m0, s49, 0xffffff80
	s_add_u32 s28, s28, 0x100
	s_addc_u32 s29, s29, 0
	global_load_lds_dwordx4 v[216:217], off offset:128
	s_add_i32 m0, s50, 0xffffff80
	s_add_u32 s27, s27, 0x100
	s_addc_u32 s44, s44, 0
	global_load_lds_dwordx4 v[218:219], off offset:128
	s_waitcnt vmcnt(8) lgkmcnt(0)
	s_barrier
	s_setprio 1
	v_mfma_f32_16x16x32_bf16 v[64:67], v[108:111], v[164:167], v[64:67]
	v_mfma_f32_16x16x32_bf16 v[60:63], v[124:127], v[164:167], v[60:63]
	v_mfma_f32_16x16x32_bf16 v[48:51], v[108:111], v[172:175], v[48:51]
	v_mfma_f32_16x16x32_bf16 v[44:47], v[124:127], v[172:175], v[44:47]
	v_mfma_f32_16x16x32_bf16 v[32:35], v[108:111], v[180:183], v[32:35]
	v_mfma_f32_16x16x32_bf16 v[28:31], v[124:127], v[180:183], v[28:31]
	v_mfma_f32_16x16x32_bf16 v[16:19], v[108:111], v[188:191], v[16:19]
	v_mfma_f32_16x16x32_bf16 v[12:15], v[124:127], v[188:191], v[12:15]
	v_mfma_f32_16x16x32_bf16 v[64:67], v[112:115], v[168:171], v[64:67]
	v_mfma_f32_16x16x32_bf16 v[60:63], v[128:131], v[168:171], v[60:63]
	v_mfma_f32_16x16x32_bf16 v[48:51], v[112:115], v[176:179], v[48:51]
	v_mfma_f32_16x16x32_bf16 v[44:47], v[128:131], v[176:179], v[44:47]
	v_mfma_f32_16x16x32_bf16 v[32:35], v[112:115], v[184:187], v[32:35]
	v_mfma_f32_16x16x32_bf16 v[28:31], v[128:131], v[184:187], v[28:31]
	v_mfma_f32_16x16x32_bf16 v[16:19], v[112:115], v[192:195], v[16:19]
	v_mfma_f32_16x16x32_bf16 v[12:15], v[128:131], v[192:195], v[12:15]
	s_setprio 0
	s_setprio 1
	v_mfma_f32_16x16x32_bf16 v[56:59], v[132:135], v[164:167], v[56:59]
	v_mfma_f32_16x16x32_bf16 v[52:55], v[148:151], v[164:167], v[52:55]
	v_mfma_f32_16x16x32_bf16 v[40:43], v[132:135], v[172:175], v[40:43]
	v_mfma_f32_16x16x32_bf16 v[36:39], v[148:151], v[172:175], v[36:39]
	v_mfma_f32_16x16x32_bf16 v[24:27], v[132:135], v[180:183], v[24:27]
	v_mfma_f32_16x16x32_bf16 v[20:23], v[148:151], v[180:183], v[20:23]
	v_mfma_f32_16x16x32_bf16 v[8:11], v[132:135], v[188:191], v[8:11]
	v_mfma_f32_16x16x32_bf16 v[4:7], v[148:151], v[188:191], v[4:7]
	v_mfma_f32_16x16x32_bf16 v[56:59], v[140:143], v[168:171], v[56:59]
	v_mfma_f32_16x16x32_bf16 v[52:55], v[156:159], v[168:171], v[52:55]
	v_mfma_f32_16x16x32_bf16 v[40:43], v[140:143], v[176:179], v[40:43]
	v_mfma_f32_16x16x32_bf16 v[36:39], v[156:159], v[176:179], v[36:39]
	v_mfma_f32_16x16x32_bf16 v[24:27], v[140:143], v[184:187], v[24:27]
	v_mfma_f32_16x16x32_bf16 v[20:23], v[156:159], v[184:187], v[20:23]
	v_mfma_f32_16x16x32_bf16 v[8:11], v[140:143], v[192:195], v[8:11]
	v_mfma_f32_16x16x32_bf16 v[4:7], v[156:159], v[192:195], v[4:7]
	s_setprio 0
	s_barrier
	s_add_i32 s45, s45, 2
	s_cmp_gt_u32 s45, 13
	s_cbranch_scc0 .LBB0_329
	s_and_b64 vcc, exec, s[14:15]
	s_cbranch_vccz .LBB0_332
	s_barrier

; #define PG8_STAGE(bufoff, gbase, voff) do { _Pragma("unroll") for (int _i = 0; _i < 2; ++_i) \
;         __builtin_amdgcn_global_load_lds((const unsigned*)((const char*)(gbase) + (voff)[_i]), (PG8_LAS unsigned*)(lds + (bufoff) + ldsw + _i * 8192), 16, 0, 0); } while (0)
; #define PG8_LDA(dst, b, h) do { _Pragma("unroll") for (int m = 0; m < 4; ++m) _Pragma("unroll") for (int k = 0; k < 2; ++k) dst[m][k] = *(const PG8_LAS bf16x8*)(lds + PG8_SA(b, h) + aoff + m * 2048 + k * 1024); } while (0)
; #define PG8_LDB(dst, b, h) do { _Pragma("unroll") for (int n = 0; n < 2; ++n) _Pragma("unroll") for (int k = 0; k < 2; ++k) dst[n][k] = *(const PG8_LAS bf16x8*)(lds + PG8_SB(b, h) + boff + n * 2048 + k * 1024); } while (0)
; #define PG8_MMA(ai, bj, At, Bt) do { __builtin_amdgcn_s_setprio(1); _Pragma("unroll") for (int m = 0; m < 4; ++m) _Pragma("unroll") for (int n = 0; n < 2; ++n) _Pragma("unroll") for (int k = 0; k < 2; ++k) \
;         acc[ai][bj][m][n] = __builtin_amdgcn_mfma_f32_16x16x32_bf16(Bt[n][k], At[m][k], acc[ai][bj][m][n], 0, 0, 0); __builtin_amdgcn_s_setprio(0); } while (0)
; #define PG8_WAIT_V(n) asm volatile("s_waitcnt vmcnt(" #n ")" ::: "memory")
; #define PG8_WAIT_L(n) asm volatile("s_waitcnt lgkmcnt(" #n ")" ::: "memory")
; #define PG8_BAR __builtin_amdgcn_s_barrier()
; #define PG8_SCHED __builtin_amdgcn_sched_barrier(0)
; template <class Epi, class Sched, bool ALIGN_EPI = false, bool SP2 = false>
; __device__ __forceinline__ void gemm_phase(PG8_LAS unsigned char* lds, const Gemm g, const Sched& S, const Epi& E) {
;     ...
;             PG8_LDB(B0, 0, 0); PG8_LDB(B1, 0, 1); PG8_SCHED; PG8_LDA(At, 0, 0); PG8_STAGE(PG8_SA(1, 1), a1 + hstep, voffA);
;             PG8_WAIT_V(8); PG8_WAIT_L(0); PG8_BAR; PG8_MMA(0, 0, At, B0); PG8_MMA(0, 1, At, B1); PG8_BAR; PG8_SCHED;
;             PG8_LDA(At, 0, 1); PG8_STAGE(PG8_SB(0, 0), b2, voffB); PG8_STAGE(PG8_SB(0, 1), b2 + hstep, voffB); PG8_STAGE(PG8_SA(0, 0), a2, voffA);
;             PG8_WAIT_V(8); PG8_WAIT_L(0); PG8_BAR; PG8_MMA(1, 0, At, B0); PG8_MMA(1, 1, At, B1); PG8_BAR; PG8_SCHED;
.LBB0_405:
	s_add_u32 s24, s8, 0xfffc0080
	s_addc_u32 s25, s9, -1
	s_add_i32 s47, 0, 0x10000
	s_cmp_eq_u32 s46, 12
	s_cselect_b32 s27, s7, s25
	s_cselect_b32 s26, s17, s24
	s_cselect_b32 s25, s19, s45
	s_cselect_b32 s24, s43, s44
	s_add_i32 s50, 0, 0x14000
	v_add_u32_e32 v156, s47, v164
	v_add_u32_e32 v167, s50, v164
	ds_read_b128 v[144:147], v156
	ds_read_b128 v[148:151], v156 offset:1024
	ds_read_b128 v[152:155], v156 offset:2048
	ds_read_b128 v[156:159], v156 offset:3072
	ds_read_b128 v[160:163], v167
	ds_read_b128 v[168:171], v167 offset:1024
	ds_read_b128 v[172:175], v167 offset:2048
	ds_read_b128 v[176:179], v167 offset:3072
	v_lshl_add_u64 v[198:199], s[8:9], 0, v[140:141]
	s_add_i32 m0, s37, 0xc000
	ds_read_b128 v[180:183], v166
	ds_read_b128 v[184:187], v166 offset:1024
	ds_read_b128 v[188:191], v166 offset:2048
	ds_read_b128 v[192:195], v166 offset:3072
	ds_read_b128 v[202:205], v166 offset:4096
	ds_read_b128 v[206:209], v166 offset:5120
	ds_read_b128 v[210:213], v166 offset:6144
	ds_read_b128 v[214:217], v166 offset:7168
	global_load_lds_dwordx4 v[198:199], off
	s_add_i32 m0, s37, 0xe000
	v_lshl_add_u64 v[198:199], s[8:9], 0, v[142:143]
	global_load_lds_dwordx4 v[198:199], off
	s_waitcnt vmcnt(8) lgkmcnt(0)
	s_barrier
	s_setprio 1
	v_mfma_f32_16x16x32_bf16 v[128:131], v[144:147], v[180:183], v[128:131]
	v_mfma_f32_16x16x32_bf16 v[120:123], v[152:155], v[180:183], v[120:123]
	v_mfma_f32_16x16x32_bf16 v[112:115], v[144:147], v[188:191], v[112:115]
	v_mfma_f32_16x16x32_bf16 v[104:107], v[152:155], v[188:191], v[104:107]
	v_mfma_f32_16x16x32_bf16 v[96:99], v[144:147], v[202:205], v[96:99]
	v_mfma_f32_16x16x32_bf16 v[88:91], v[152:155], v[202:205], v[88:91]
	v_mfma_f32_16x16x32_bf16 v[80:83], v[144:147], v[210:213], v[80:83]
	v_mfma_f32_16x16x32_bf16 v[72:75], v[152:155], v[210:213], v[72:75]
	v_mfma_f32_16x16x32_bf16 v[128:131], v[148:151], v[184:187], v[128:131]
	v_mfma_f32_16x16x32_bf16 v[120:123], v[156:159], v[184:187], v[120:123]
	v_mfma_f32_16x16x32_bf16 v[112:115], v[148:151], v[192:195], v[112:115]
	v_mfma_f32_16x16x32_bf16 v[104:107], v[156:159], v[192:195], v[104:107]
	v_mfma_f32_16x16x32_bf16 v[96:99], v[148:151], v[206:209], v[96:99]
	v_mfma_f32_16x16x32_bf16 v[88:91], v[156:159], v[206:209], v[88:91]
	v_mfma_f32_16x16x32_bf16 v[80:83], v[148:151], v[214:217], v[80:83]
	v_mfma_f32_16x16x32_bf16 v[72:75], v[156:159], v[214:217], v[72:75]
	s_setprio 0
	s_setprio 1
	v_mfma_f32_16x16x32_bf16 v[124:127], v[160:163], v[180:183], v[124:127]
	v_mfma_f32_16x16x32_bf16 v[116:119], v[172:175], v[180:183], v[116:119]
	v_mfma_f32_16x16x32_bf16 v[108:111], v[160:163], v[188:191], v[108:111]
	v_mfma_f32_16x16x32_bf16 v[100:103], v[172:175], v[188:191], v[100:103]
	v_mfma_f32_16x16x32_bf16 v[92:95], v[160:163], v[202:205], v[92:95]
	v_mfma_f32_16x16x32_bf16 v[84:87], v[172:175], v[202:205], v[84:87]
	v_mfma_f32_16x16x32_bf16 v[76:79], v[160:163], v[210:213], v[76:79]
	v_mfma_f32_16x16x32_bf16 v[68:71], v[172:175], v[210:213], v[68:71]
	v_mfma_f32_16x16x32_bf16 v[124:127], v[168:171], v[184:187], v[124:127]
	v_mfma_f32_16x16x32_bf16 v[116:119], v[176:179], v[184:187], v[116:119]
	v_mfma_f32_16x16x32_bf16 v[108:111], v[168:171], v[192:195], v[108:111]
	v_mfma_f32_16x16x32_bf16 v[100:103], v[176:179], v[192:195], v[100:103]
	v_mfma_f32_16x16x32_bf16 v[92:95], v[168:171], v[206:209], v[92:95]
	v_mfma_f32_16x16x32_bf16 v[84:87], v[176:179], v[206:209], v[84:87]
	v_mfma_f32_16x16x32_bf16 v[76:79], v[168:171], v[214:217], v[76:79]
	v_mfma_f32_16x16x32_bf16 v[68:71], v[176:179], v[214:217], v[68:71]
	s_setprio 0
	s_barrier
	s_add_i32 s47, s47, s35
	v_lshl_add_u64 v[198:199], s[24:25], 0, v[134:135]
	s_mov_b32 m0, s47
	ds_read_b128 v[180:183], v166 offset:16384
	ds_read_b128 v[184:187], v166 offset:17408
	ds_read_b128 v[188:191], v166 offset:18432
	ds_read_b128 v[192:195], v166 offset:19456
	ds_read_b128 v[202:205], v166 offset:20480
	ds_read_b128 v[206:209], v166 offset:21504
	ds_read_b128 v[210:213], v166 offset:22528
	ds_read_b128 v[214:217], v166 offset:23552
	global_load_lds_dwordx4 v[198:199], off
	s_add_i32 m0, s47, 0x2000
	s_add_u32 s48, s24, 0x40000
	v_lshl_add_u64 v[218:219], s[24:25], 0, v[0:1]
	s_addc_u32 s49, s25, 0
	s_add_i32 s47, s50, s35
	global_load_lds_dwordx4 v[218:219], off
	v_lshl_add_u64 v[220:221], s[48:49], 0, v[134:135]
	s_mov_b32 m0, s47
	v_lshl_add_u64 v[222:223], s[26:27], 0, v[132:133]
	global_load_lds_dwordx4 v[220:221], off
	s_add_i32 m0, s47, 0x2000
	v_lshl_add_u64 v[220:221], s[48:49], 0, v[0:1]
	global_load_lds_dwordx4 v[220:221], off
	s_mov_b32 m0, s37
	v_lshl_add_u64 v[220:221], s[26:27], 0, v[136:137]
	global_load_lds_dwordx4 v[220:221], off
	s_mov_b32 m0, s38
	s_add_i32 s47, 0, 0x18000
	global_load_lds_dwordx4 v[222:223], off
	s_waitcnt vmcnt(8) lgkmcnt(0)
	s_barrier
; #define PG8_STAGE(bufoff, gbase, voff) do { _Pragma("unroll") for (int _i = 0; _i < 2; ++_i) \
;         __builtin_amdgcn_global_load_lds((const unsigned*)((const char*)(gbase) + (voff)[_i]), (PG8_LAS unsigned*)(lds + (bufoff) + ldsw + _i * 8192), 16, 0, 0); } while (0)
; #define PG8_LDA(dst, b, h) do { _Pragma("unroll") for (int m = 0; m < 4; ++m) _Pragma("unroll") for (int k = 0; k < 2; ++k) dst[m][k] = *(const PG8_LAS bf16x8*)(lds + PG8_SA(b, h) + aoff + m * 2048 + k * 1024); } while (0)
; #define PG8_LDB(dst, b, h) do { _Pragma("unroll") for (int n = 0; n < 2; ++n) _Pragma("unroll") for (int k = 0; k < 2; ++k) dst[n][k] = *(const PG8_LAS bf16x8*)(lds + PG8_SB(b, h) + boff + n * 2048 + k * 1024); } while (0)
; #define PG8_MMA(ai, bj, At, Bt) do { __builtin_amdgcn_s_setprio(1); _Pragma("unroll") for (int m = 0; m < 4; ++m) _Pragma("unroll") for (int n = 0; n < 2; ++n) _Pragma("unroll") for (int k = 0; k < 2; ++k) \
;         acc[ai][bj][m][n] = __builtin_amdgcn_mfma_f32_16x16x32_bf16(Bt[n][k], At[m][k], acc[ai][bj][m][n], 0, 0, 0); __builtin_amdgcn_s_setprio(0); } while (0)
; #define PG8_WAIT_V(n) asm volatile("s_waitcnt vmcnt(" #n ")" ::: "memory")
; #define PG8_WAIT_L(n) asm volatile("s_waitcnt lgkmcnt(" #n ")" ::: "memory")
; #define PG8_BAR __builtin_amdgcn_s_barrier()
; #define PG8_SCHED __builtin_amdgcn_sched_barrier(0)
; template <class Epi, class Sched, bool ALIGN_EPI = false, bool SP2 = false>
; __device__ __forceinline__ void gemm_phase(PG8_LAS unsigned char* lds, const Gemm g, const Sched& S, const Epi& E) {
;     ...
;             PG8_WAIT_V(8); PG8_WAIT_L(0); PG8_BAR; PG8_MMA(1, 0, At, B0); PG8_MMA(1, 1, At, B1); PG8_BAR; PG8_SCHED;
;             PG8_LDB(B0, 1, 0); PG8_LDB(B1, 1, 1); PG8_SCHED; PG8_LDA(At, 1, 0); PG8_STAGE(PG8_SA(0, 1), a2 + hstep, voffA);
;             PG8_WAIT_V(8); PG8_WAIT_L(0); PG8_BAR; PG8_MMA(0, 0, At, B0); PG8_MMA(0, 1, At, B1); PG8_BAR; PG8_SCHED;
	s_setprio 1
	v_mfma_f32_16x16x32_bf16 v[64:67], v[144:147], v[180:183], v[64:67]
	v_mfma_f32_16x16x32_bf16 v[56:59], v[152:155], v[180:183], v[56:59]
	v_mfma_f32_16x16x32_bf16 v[48:51], v[144:147], v[188:191], v[48:51]
	v_mfma_f32_16x16x32_bf16 v[40:43], v[152:155], v[188:191], v[40:43]
	v_mfma_f32_16x16x32_bf16 v[32:35], v[144:147], v[202:205], v[32:35]
	v_mfma_f32_16x16x32_bf16 v[24:27], v[152:155], v[202:205], v[24:27]
	v_mfma_f32_16x16x32_bf16 v[16:19], v[144:147], v[210:213], v[16:19]
	v_mfma_f32_16x16x32_bf16 v[8:11], v[152:155], v[210:213], v[8:11]
	v_mfma_f32_16x16x32_bf16 v[64:67], v[148:151], v[184:187], v[64:67]
	v_mfma_f32_16x16x32_bf16 v[56:59], v[156:159], v[184:187], v[56:59]
	v_mfma_f32_16x16x32_bf16 v[48:51], v[148:151], v[192:195], v[48:51]
	v_mfma_f32_16x16x32_bf16 v[40:43], v[156:159], v[192:195], v[40:43]
	v_mfma_f32_16x16x32_bf16 v[32:35], v[148:151], v[206:209], v[32:35]
	v_mfma_f32_16x16x32_bf16 v[24:27], v[156:159], v[206:209], v[24:27]
	v_mfma_f32_16x16x32_bf16 v[16:19], v[148:151], v[214:217], v[16:19]
	v_mfma_f32_16x16x32_bf16 v[8:11], v[156:159], v[214:217], v[8:11]
	s_setprio 0
	s_setprio 1
	v_mfma_f32_16x16x32_bf16 v[60:63], v[160:163], v[180:183], v[60:63]
	v_mfma_f32_16x16x32_bf16 v[52:55], v[172:175], v[180:183], v[52:55]
	v_mfma_f32_16x16x32_bf16 v[44:47], v[160:163], v[188:191], v[44:47]
	v_mfma_f32_16x16x32_bf16 v[36:39], v[172:175], v[188:191], v[36:39]
	v_mfma_f32_16x16x32_bf16 v[28:31], v[160:163], v[202:205], v[28:31]
	v_mfma_f32_16x16x32_bf16 v[20:23], v[172:175], v[202:205], v[20:23]
	v_mfma_f32_16x16x32_bf16 v[12:15], v[160:163], v[210:213], v[12:15]
	v_mfma_f32_16x16x32_bf16 v[4:7], v[172:175], v[210:213], v[4:7]
	v_mfma_f32_16x16x32_bf16 v[60:63], v[168:171], v[184:187], v[60:63]
	v_mfma_f32_16x16x32_bf16 v[52:55], v[176:179], v[184:187], v[52:55]
	v_mfma_f32_16x16x32_bf16 v[44:47], v[168:171], v[192:195], v[44:47]
	v_mfma_f32_16x16x32_bf16 v[36:39], v[176:179], v[192:195], v[36:39]
	v_mfma_f32_16x16x32_bf16 v[28:31], v[168:171], v[206:209], v[28:31]
	v_mfma_f32_16x16x32_bf16 v[20:23], v[176:179], v[206:209], v[20:23]
	v_mfma_f32_16x16x32_bf16 v[12:15], v[168:171], v[214:217], v[12:15]
	v_mfma_f32_16x16x32_bf16 v[4:7], v[176:179], v[214:217], v[4:7]
	s_setprio 0
	s_barrier
	s_add_i32 s48, 0, 0x1c000
	v_add_u32_e32 v156, s47, v164
	v_add_u32_e32 v167, s48, v164
	ds_read_b128 v[144:147], v156
	ds_read_b128 v[148:151], v156 offset:1024
	ds_read_b128 v[152:155], v156 offset:2048
	ds_read_b128 v[156:159], v156 offset:3072
	ds_read_b128 v[160:163], v167
	ds_read_b128 v[168:171], v167 offset:1024
	ds_read_b128 v[172:175], v167 offset:2048
	ds_read_b128 v[176:179], v167 offset:3072
	s_add_u32 s26, s26, 0x40000
	s_addc_u32 s27, s27, 0
	s_mov_b32 m0, s39
	v_lshl_add_u64 v[224:225], s[26:27], 0, v[136:137]
	ds_read_b128 v[180:183], v166 offset:32768
	ds_read_b128 v[184:187], v166 offset:33792
	ds_read_b128 v[188:191], v166 offset:34816
	ds_read_b128 v[192:195], v166 offset:35840
	ds_read_b128 v[202:205], v166 offset:36864
	ds_read_b128 v[206:209], v166 offset:37888
	ds_read_b128 v[210:213], v166 offset:38912
	ds_read_b128 v[214:217], v166 offset:39936
	global_load_lds_dwordx4 v[224:225], off
	s_mov_b32 m0, s40
	v_lshl_add_u64 v[224:225], s[26:27], 0, v[132:133]
	global_load_lds_dwordx4 v[224:225], off
	s_waitcnt vmcnt(8) lgkmcnt(0)
	s_barrier
	s_setprio 1
	v_mfma_f32_16x16x32_bf16 v[128:131], v[144:147], v[180:183], v[128:131]
	v_mfma_f32_16x16x32_bf16 v[120:123], v[152:155], v[180:183], v[120:123]
	v_mfma_f32_16x16x32_bf16 v[112:115], v[144:147], v[188:191], v[112:115]
	v_mfma_f32_16x16x32_bf16 v[104:107], v[152:155], v[188:191], v[104:107]
	v_mfma_f32_16x16x32_bf16 v[96:99], v[144:147], v[202:205], v[96:99]
	v_mfma_f32_16x16x32_bf16 v[88:91], v[152:155], v[202:205], v[88:91]
	v_mfma_f32_16x16x32_bf16 v[80:83], v[144:147], v[210:213], v[80:83]
	v_mfma_f32_16x16x32_bf16 v[72:75], v[152:155], v[210:213], v[72:75]
	v_mfma_f32_16x16x32_bf16 v[128:131], v[148:151], v[184:187], v[128:131]
	v_mfma_f32_16x16x32_bf16 v[120:123], v[156:159], v[184:187], v[120:123]
	v_mfma_f32_16x16x32_bf16 v[112:115], v[148:151], v[192:195], v[112:115]
	v_mfma_f32_16x16x32_bf16 v[104:107], v[156:159], v[192:195], v[104:107]
	v_mfma_f32_16x16x32_bf16 v[96:99], v[148:151], v[206:209], v[96:99]
	v_mfma_f32_16x16x32_bf16 v[88:91], v[156:159], v[206:209], v[88:91]
	v_mfma_f32_16x16x32_bf16 v[80:83], v[148:151], v[214:217], v[80:83]
	v_mfma_f32_16x16x32_bf16 v[72:75], v[156:159], v[214:217], v[72:75]
	s_setprio 0
	s_setprio 1
	v_mfma_f32_16x16x32_bf16 v[124:127], v[160:163], v[180:183], v[124:127]
	v_mfma_f32_16x16x32_bf16 v[116:119], v[172:175], v[180:183], v[116:119]
	v_mfma_f32_16x16x32_bf16 v[108:111], v[160:163], v[188:191], v[108:111]
	v_mfma_f32_16x16x32_bf16 v[100:103], v[172:175], v[188:191], v[100:103]
	v_mfma_f32_16x16x32_bf16 v[92:95], v[160:163], v[202:205], v[92:95]
	v_mfma_f32_16x16x32_bf16 v[84:87], v[172:175], v[202:205], v[84:87]
	v_mfma_f32_16x16x32_bf16 v[76:79], v[160:163], v[210:213], v[76:79]
	v_mfma_f32_16x16x32_bf16 v[68:71], v[172:175], v[210:213], v[68:71]
	v_mfma_f32_16x16x32_bf16 v[124:127], v[168:171], v[184:187], v[124:127]
	v_mfma_f32_16x16x32_bf16 v[116:119], v[176:179], v[184:187], v[116:119]
	v_mfma_f32_16x16x32_bf16 v[108:111], v[168:171], v[192:195], v[108:111]
	v_mfma_f32_16x16x32_bf16 v[100:103], v[176:179], v[192:195], v[100:103]
	v_mfma_f32_16x16x32_bf16 v[92:95], v[168:171], v[206:209], v[92:95]
	v_mfma_f32_16x16x32_bf16 v[84:87], v[176:179], v[206:209], v[84:87]
	v_mfma_f32_16x16x32_bf16 v[76:79], v[168:171], v[214:217], v[76:79]
	v_mfma_f32_16x16x32_bf16 v[68:71], v[176:179], v[214:217], v[68:71]
	s_setprio 0
	s_barrier
; #define PG8_STAGE(bufoff, gbase, voff) do { _Pragma("unroll") for (int _i = 0; _i < 2; ++_i) \
;         __builtin_amdgcn_global_load_lds((const unsigned*)((const char*)(gbase) + (voff)[_i]), (PG8_LAS unsigned*)(lds + (bufoff) + ldsw + _i * 8192), 16, 0, 0); } while (0)
; #define PG8_LDA(dst, b, h) do { _Pragma("unroll") for (int m = 0; m < 4; ++m) _Pragma("unroll") for (int k = 0; k < 2; ++k) dst[m][k] = *(const PG8_LAS bf16x8*)(lds + PG8_SA(b, h) + aoff + m * 2048 + k * 1024); } while (0)
; #define PG8_MMA(ai, bj, At, Bt) do { __builtin_amdgcn_s_setprio(1); _Pragma("unroll") for (int m = 0; m < 4; ++m) _Pragma("unroll") for (int n = 0; n < 2; ++n) _Pragma("unroll") for (int k = 0; k < 2; ++k) \
;         acc[ai][bj][m][n] = __builtin_amdgcn_mfma_f32_16x16x32_bf16(Bt[n][k], At[m][k], acc[ai][bj][m][n], 0, 0, 0); __builtin_amdgcn_s_setprio(0); } while (0)
; #define PG8_WAIT_V(n) asm volatile("s_waitcnt vmcnt(" #n ")" ::: "memory")
; #define PG8_WAIT_L(n) asm volatile("s_waitcnt lgkmcnt(" #n ")" ::: "memory")
; #define PG8_BAR __builtin_amdgcn_s_barrier()
; #define PG8_SCHED __builtin_amdgcn_sched_barrier(0)
; template <class Epi, class Sched, bool ALIGN_EPI = false, bool SP2 = false>
; __device__ __forceinline__ void gemm_phase(PG8_LAS unsigned char* lds, const Gemm g, const Sched& S, const Epi& E) {
;     ...
;             PG8_LDA(At, 1, 1); PG8_STAGE(PG8_SB(1, 0), b3, voffB); PG8_STAGE(PG8_SB(1, 1), b3 + hstep, voffB); PG8_STAGE(PG8_SA(1, 0), a3, voffA);
;             PG8_WAIT_V(8); PG8_WAIT_L(0); PG8_BAR; PG8_MMA(1, 0, At, B0); PG8_MMA(1, 1, At, B1); PG8_BAR; PG8_SCHED;
	s_add_i32 s26, s47, s35
	s_add_i32 m0, s26, 0xffffff80
	ds_read_b128 v[180:183], v166 offset:49152
	ds_read_b128 v[184:187], v166 offset:50176
	ds_read_b128 v[188:191], v166 offset:51200
	ds_read_b128 v[192:195], v166 offset:52224
	ds_read_b128 v[202:205], v166 offset:53248
	ds_read_b128 v[206:209], v166 offset:54272
	ds_read_b128 v[210:213], v166 offset:55296
	ds_read_b128 v[214:217], v166 offset:56320
	global_load_lds_dwordx4 v[198:199], off offset:128
	s_add_i32 m0, s26, 0x1f80
	s_add_u32 s24, s24, 0x40080
	s_addc_u32 s25, s25, 0
	s_add_i32 s26, s48, s35
	global_load_lds_dwordx4 v[218:219], off offset:128
	s_mov_b32 m0, s26
	v_lshl_add_u64 v[198:199], s[24:25], 0, v[134:135]
	global_load_lds_dwordx4 v[198:199], off
	s_add_i32 m0, s26, 0x2000
	v_lshl_add_u64 v[198:199], s[24:25], 0, v[0:1]
	global_load_lds_dwordx4 v[198:199], off
	s_add_i32 m0, s41, 0xffffff80
	s_add_u32 s8, s8, 0x100
	s_addc_u32 s9, s9, 0
	global_load_lds_dwordx4 v[220:221], off offset:128
	s_add_i32 m0, s42, 0xffffff80
	s_add_u32 s44, s44, 0x100
	s_addc_u32 s45, s45, 0
	global_load_lds_dwordx4 v[222:223], off offset:128
	s_waitcnt vmcnt(8) lgkmcnt(0)
	s_barrier
	s_setprio 1
	v_mfma_f32_16x16x32_bf16 v[64:67], v[144:147], v[180:183], v[64:67]
	v_mfma_f32_16x16x32_bf16 v[56:59], v[152:155], v[180:183], v[56:59]
	v_mfma_f32_16x16x32_bf16 v[48:51], v[144:147], v[188:191], v[48:51]
	v_mfma_f32_16x16x32_bf16 v[40:43], v[152:155], v[188:191], v[40:43]
	v_mfma_f32_16x16x32_bf16 v[32:35], v[144:147], v[202:205], v[32:35]
	v_mfma_f32_16x16x32_bf16 v[24:27], v[152:155], v[202:205], v[24:27]
	v_mfma_f32_16x16x32_bf16 v[16:19], v[144:147], v[210:213], v[16:19]
	v_mfma_f32_16x16x32_bf16 v[8:11], v[152:155], v[210:213], v[8:11]
	v_mfma_f32_16x16x32_bf16 v[64:67], v[148:151], v[184:187], v[64:67]
	v_mfma_f32_16x16x32_bf16 v[56:59], v[156:159], v[184:187], v[56:59]
	v_mfma_f32_16x16x32_bf16 v[48:51], v[148:151], v[192:195], v[48:51]
	v_mfma_f32_16x16x32_bf16 v[40:43], v[156:159], v[192:195], v[40:43]
	v_mfma_f32_16x16x32_bf16 v[32:35], v[148:151], v[206:209], v[32:35]
	v_mfma_f32_16x16x32_bf16 v[24:27], v[156:159], v[206:209], v[24:27]
	v_mfma_f32_16x16x32_bf16 v[16:19], v[148:151], v[214:217], v[16:19]
	v_mfma_f32_16x16x32_bf16 v[8:11], v[156:159], v[214:217], v[8:11]
	s_setprio 0
	s_setprio 1
	v_mfma_f32_16x16x32_bf16 v[60:63], v[160:163], v[180:183], v[60:63]
	v_mfma_f32_16x16x32_bf16 v[52:55], v[172:175], v[180:183], v[52:55]
	v_mfma_f32_16x16x32_bf16 v[44:47], v[160:163], v[188:191], v[44:47]
	v_mfma_f32_16x16x32_bf16 v[36:39], v[172:175], v[188:191], v[36:39]
	v_mfma_f32_16x16x32_bf16 v[28:31], v[160:163], v[202:205], v[28:31]
	v_mfma_f32_16x16x32_bf16 v[20:23], v[172:175], v[202:205], v[20:23]
	v_mfma_f32_16x16x32_bf16 v[12:15], v[160:163], v[210:213], v[12:15]
	v_mfma_f32_16x16x32_bf16 v[4:7], v[172:175], v[210:213], v[4:7]
	v_mfma_f32_16x16x32_bf16 v[60:63], v[168:171], v[184:187], v[60:63]
	v_mfma_f32_16x16x32_bf16 v[52:55], v[176:179], v[184:187], v[52:55]
	v_mfma_f32_16x16x32_bf16 v[44:47], v[168:171], v[192:195], v[44:47]
	v_mfma_f32_16x16x32_bf16 v[36:39], v[176:179], v[192:195], v[36:39]
	v_mfma_f32_16x16x32_bf16 v[28:31], v[168:171], v[206:209], v[28:31]
	v_mfma_f32_16x16x32_bf16 v[20:23], v[176:179], v[206:209], v[20:23]
	v_mfma_f32_16x16x32_bf16 v[12:15], v[168:171], v[214:217], v[12:15]
	v_mfma_f32_16x16x32_bf16 v[4:7], v[176:179], v[214:217], v[4:7]
	s_setprio 0
	s_barrier
	s_add_i32 s46, s46, 2
	s_cmp_gt_u32 s46, 13
	s_cbranch_scc0 .LBB0_405
	s_and_b64 vcc, exec, s[14:15]
	s_cbranch_vccz .LBB0_408
	s_barrier

; #define PG8_STAGE(bufoff, gbase, voff) do { _Pragma("unroll") for (int _i = 0; _i < 2; ++_i) \
;         __builtin_amdgcn_global_load_lds((const unsigned*)((const char*)(gbase) + (voff)[_i]), (PG8_LAS unsigned*)(lds + (bufoff) + ldsw + _i * 8192), 16, 0, 0); } while (0)
; #define PG8_LDA(dst, b, h) do { _Pragma("unroll") for (int m = 0; m < 4; ++m) _Pragma("unroll") for (int k = 0; k < 2; ++k) dst[m][k] = *(const PG8_LAS bf16x8*)(lds + PG8_SA(b, h) + aoff + m * 2048 + k * 1024); } while (0)
; #define PG8_LDB(dst, b, h) do { _Pragma("unroll") for (int n = 0; n < 2; ++n) _Pragma("unroll") for (int k = 0; k < 2; ++k) dst[n][k] = *(const PG8_LAS bf16x8*)(lds + PG8_SB(b, h) + boff + n * 2048 + k * 1024); } while (0)
; #define PG8_MMA(ai, bj, At, Bt) do { __builtin_amdgcn_s_setprio(1); _Pragma("unroll") for (int m = 0; m < 4; ++m) _Pragma("unroll") for (int n = 0; n < 2; ++n) _Pragma("unroll") for (int k = 0; k < 2; ++k) \
;         acc[ai][bj][m][n] = __builtin_amdgcn_mfma_f32_16x16x32_bf16(Bt[n][k], At[m][k], acc[ai][bj][m][n], 0, 0, 0); __builtin_amdgcn_s_setprio(0); } while (0)
; #define PG8_WAIT_V(n) asm volatile("s_waitcnt vmcnt(" #n ")" ::: "memory")
; #define PG8_WAIT_L(n) asm volatile("s_waitcnt lgkmcnt(" #n ")" ::: "memory")
; #define PG8_BAR __builtin_amdgcn_s_barrier()
; #define PG8_SCHED __builtin_amdgcn_sched_barrier(0)
; template <class Epi, class Sched, bool ALIGN_EPI = false, bool SP2 = false>
; __device__ __forceinline__ void gemm_phase(PG8_LAS unsigned char* lds, const Gemm g, const Sched& S, const Epi& E) {
;     ...
;             PG8_LDB(B0, 0, 0); PG8_LDB(B1, 0, 1); PG8_SCHED; PG8_LDA(At, 0, 0); PG8_STAGE(PG8_SA(1, 1), a1 + hstep, voffA);
;             PG8_WAIT_V(8); PG8_WAIT_L(0); PG8_BAR; PG8_MMA(0, 0, At, B0); PG8_MMA(0, 1, At, B1); PG8_BAR; PG8_SCHED;
;             PG8_LDA(At, 0, 1); PG8_STAGE(PG8_SB(0, 0), b2, voffB); PG8_STAGE(PG8_SB(0, 1), b2 + hstep, voffB); PG8_STAGE(PG8_SA(0, 0), a2, voffA);
;             PG8_WAIT_V(8); PG8_WAIT_L(0); PG8_BAR; PG8_MMA(1, 0, At, B0); PG8_MMA(1, 1, At, B1); PG8_BAR; PG8_SCHED;
.LBB0_480:
	s_add_u32 s8, s26, 0x100
	s_addc_u32 s9, s27, 0
	s_add_i32 s54, 0, 0x10000
	s_cmp_eq_u32 s53, 40
	s_cselect_b32 s31, s23, s9
	s_cselect_b32 s30, s22, s8
	s_cselect_b32 s29, s25, s45
	s_cselect_b32 s28, s24, s44
	s_add_i32 s55, 0, 0x14000
	v_add_u32_e32 v100, s54, v234
	v_add_u32_e32 v144, s55, v234
	ds_read_b128 v[68:71], v100
	ds_read_b128 v[80:83], v100 offset:1024
	ds_read_b128 v[92:95], v100 offset:2048
	ds_read_b128 v[100:103], v100 offset:3072
	ds_read_b128 v[112:115], v144
	ds_read_b128 v[120:123], v144 offset:1024
	ds_read_b128 v[132:135], v144 offset:2048
	ds_read_b128 v[144:147], v144 offset:3072
	v_lshl_add_u64 v[198:199], s[26:27], 0, v[204:205]
	s_add_i32 m0, s40, 0xc000
	ds_read_b128 v[156:159], v236
	ds_read_b128 v[168:171], v236 offset:1024
	ds_read_b128 v[172:175], v236 offset:2048
	ds_read_b128 v[176:179], v236 offset:3072
	ds_read_b128 v[180:183], v236 offset:4096
	ds_read_b128 v[184:187], v236 offset:5120
	ds_read_b128 v[188:191], v236 offset:6144
	ds_read_b128 v[208:211], v236 offset:7168
	global_load_lds_dwordx4 v[198:199], off
	s_add_i32 m0, s40, 0xe000
	v_lshl_add_u64 v[198:199], s[26:27], 0, v[206:207]
	global_load_lds_dwordx4 v[198:199], off
	s_waitcnt vmcnt(8) lgkmcnt(0)
	s_barrier
	s_setprio 1
	v_mfma_f32_16x16x32_bf16 v[164:167], v[68:71], v[156:159], v[164:167]
	v_mfma_f32_16x16x32_bf16 v[160:163], v[92:95], v[156:159], v[160:163]
	v_mfma_f32_16x16x32_bf16 v[140:143], v[68:71], v[172:175], v[140:143]
	v_mfma_f32_16x16x32_bf16 v[136:139], v[92:95], v[172:175], v[136:139]
	v_mfma_f32_16x16x32_bf16 v[116:119], v[68:71], v[180:183], v[116:119]
	v_mfma_f32_16x16x32_bf16 v[108:111], v[92:95], v[180:183], v[108:111]
	v_mfma_f32_16x16x32_bf16 v[88:91], v[68:71], v[188:191], v[88:91]
	v_mfma_f32_16x16x32_bf16 v[84:87], v[92:95], v[188:191], v[84:87]
	v_mfma_f32_16x16x32_bf16 v[164:167], v[80:83], v[168:171], v[164:167]
	v_mfma_f32_16x16x32_bf16 v[160:163], v[100:103], v[168:171], v[160:163]
	v_mfma_f32_16x16x32_bf16 v[140:143], v[80:83], v[176:179], v[140:143]
	v_mfma_f32_16x16x32_bf16 v[136:139], v[100:103], v[176:179], v[136:139]
	v_mfma_f32_16x16x32_bf16 v[116:119], v[80:83], v[184:187], v[116:119]
	v_mfma_f32_16x16x32_bf16 v[108:111], v[100:103], v[184:187], v[108:111]
	v_mfma_f32_16x16x32_bf16 v[88:91], v[80:83], v[208:211], v[88:91]
	v_mfma_f32_16x16x32_bf16 v[84:87], v[100:103], v[208:211], v[84:87]
	s_setprio 0
	s_setprio 1
	v_mfma_f32_16x16x32_bf16 v[152:155], v[112:115], v[156:159], v[152:155]
	v_mfma_f32_16x16x32_bf16 v[148:151], v[132:135], v[156:159], v[148:151]
	v_mfma_f32_16x16x32_bf16 v[128:131], v[112:115], v[172:175], v[128:131]
	v_mfma_f32_16x16x32_bf16 v[124:127], v[132:135], v[172:175], v[124:127]
	v_mfma_f32_16x16x32_bf16 v[104:107], v[112:115], v[180:183], v[104:107]
	v_mfma_f32_16x16x32_bf16 v[96:99], v[132:135], v[180:183], v[96:99]
	v_mfma_f32_16x16x32_bf16 v[76:79], v[112:115], v[188:191], v[76:79]
	v_mfma_f32_16x16x32_bf16 v[72:75], v[132:135], v[188:191], v[72:75]
	v_mfma_f32_16x16x32_bf16 v[152:155], v[120:123], v[168:171], v[152:155]
	v_mfma_f32_16x16x32_bf16 v[148:151], v[144:147], v[168:171], v[148:151]
	v_mfma_f32_16x16x32_bf16 v[128:131], v[120:123], v[176:179], v[128:131]
	v_mfma_f32_16x16x32_bf16 v[124:127], v[144:147], v[176:179], v[124:127]
	v_mfma_f32_16x16x32_bf16 v[104:107], v[120:123], v[184:187], v[104:107]
	v_mfma_f32_16x16x32_bf16 v[96:99], v[144:147], v[184:187], v[96:99]
	v_mfma_f32_16x16x32_bf16 v[76:79], v[120:123], v[208:211], v[76:79]
	v_mfma_f32_16x16x32_bf16 v[72:75], v[144:147], v[208:211], v[72:75]
	s_setprio 0
	s_barrier
	s_add_i32 s26, s54, s39
	v_lshl_add_u64 v[198:199], s[28:29], 0, v[192:193]
	s_mov_b32 m0, s26
	ds_read_b128 v[156:159], v236 offset:16384
	ds_read_b128 v[168:171], v236 offset:17408
	ds_read_b128 v[172:175], v236 offset:18432
	ds_read_b128 v[176:179], v236 offset:19456
	ds_read_b128 v[180:183], v236 offset:20480
	ds_read_b128 v[184:187], v236 offset:21504
	ds_read_b128 v[188:191], v236 offset:22528
	ds_read_b128 v[208:211], v236 offset:23552
	global_load_lds_dwordx4 v[198:199], off
	s_add_i32 m0, s26, 0x2000
	s_add_u32 s26, s28, 0xb0000
	v_lshl_add_u64 v[212:213], s[28:29], 0, v[202:203]
	s_addc_u32 s27, s29, 0
	s_add_i32 s54, s55, s39
	global_load_lds_dwordx4 v[212:213], off
	v_lshl_add_u64 v[214:215], s[26:27], 0, v[192:193]
	s_mov_b32 m0, s54
	v_lshl_add_u64 v[216:217], s[30:31], 0, v[194:195]
	global_load_lds_dwordx4 v[214:215], off
	s_add_i32 m0, s54, 0x2000
	v_lshl_add_u64 v[214:215], s[26:27], 0, v[202:203]
	global_load_lds_dwordx4 v[214:215], off
	s_mov_b32 m0, s40
	v_lshl_add_u64 v[214:215], s[30:31], 0, v[0:1]
	global_load_lds_dwordx4 v[214:215], off
	s_mov_b32 m0, s41
	s_add_i32 s54, 0, 0x18000
	global_load_lds_dwordx4 v[216:217], off
	s_waitcnt vmcnt(8) lgkmcnt(0)
	s_barrier
; #define PG8_STAGE(bufoff, gbase, voff) do { _Pragma("unroll") for (int _i = 0; _i < 2; ++_i) \
;         __builtin_amdgcn_global_load_lds((const unsigned*)((const char*)(gbase) + (voff)[_i]), (PG8_LAS unsigned*)(lds + (bufoff) + ldsw + _i * 8192), 16, 0, 0); } while (0)
; #define PG8_LDA(dst, b, h) do { _Pragma("unroll") for (int m = 0; m < 4; ++m) _Pragma("unroll") for (int k = 0; k < 2; ++k) dst[m][k] = *(const PG8_LAS bf16x8*)(lds + PG8_SA(b, h) + aoff + m * 2048 + k * 1024); } while (0)
; #define PG8_LDB(dst, b, h) do { _Pragma("unroll") for (int n = 0; n < 2; ++n) _Pragma("unroll") for (int k = 0; k < 2; ++k) dst[n][k] = *(const PG8_LAS bf16x8*)(lds + PG8_SB(b, h) + boff + n * 2048 + k * 1024); } while (0)
; #define PG8_MMA(ai, bj, At, Bt) do { __builtin_amdgcn_s_setprio(1); _Pragma("unroll") for (int m = 0; m < 4; ++m) _Pragma("unroll") for (int n = 0; n < 2; ++n) _Pragma("unroll") for (int k = 0; k < 2; ++k) \
;         acc[ai][bj][m][n] = __builtin_amdgcn_mfma_f32_16x16x32_bf16(Bt[n][k], At[m][k], acc[ai][bj][m][n], 0, 0, 0); __builtin_amdgcn_s_setprio(0); } while (0)
; #define PG8_WAIT_V(n) asm volatile("s_waitcnt vmcnt(" #n ")" ::: "memory")
; #define PG8_WAIT_L(n) asm volatile("s_waitcnt lgkmcnt(" #n ")" ::: "memory")
; #define PG8_BAR __builtin_amdgcn_s_barrier()
; #define PG8_SCHED __builtin_amdgcn_sched_barrier(0)
; template <class Epi, class Sched, bool ALIGN_EPI = false, bool SP2 = false>
; __device__ __forceinline__ void gemm_phase(PG8_LAS unsigned char* lds, const Gemm g, const Sched& S, const Epi& E) {
;     ...
;             PG8_WAIT_V(8); PG8_WAIT_L(0); PG8_BAR; PG8_MMA(1, 0, At, B0); PG8_MMA(1, 1, At, B1); PG8_BAR; PG8_SCHED;
;             PG8_LDB(B0, 1, 0); PG8_LDB(B1, 1, 1); PG8_SCHED; PG8_LDA(At, 1, 0); PG8_STAGE(PG8_SA(0, 1), a2 + hstep, voffA);
;             PG8_WAIT_V(8); PG8_WAIT_L(0); PG8_BAR; PG8_MMA(0, 0, At, B0); PG8_MMA(0, 1, At, B1); PG8_BAR; PG8_SCHED;
	s_setprio 1
	v_mfma_f32_16x16x32_bf16 v[64:67], v[68:71], v[156:159], v[64:67]
	v_mfma_f32_16x16x32_bf16 v[60:63], v[92:95], v[156:159], v[60:63]
	v_mfma_f32_16x16x32_bf16 v[48:51], v[68:71], v[172:175], v[48:51]
	v_mfma_f32_16x16x32_bf16 v[44:47], v[92:95], v[172:175], v[44:47]
	v_mfma_f32_16x16x32_bf16 v[32:35], v[68:71], v[180:183], v[32:35]
	v_mfma_f32_16x16x32_bf16 v[28:31], v[92:95], v[180:183], v[28:31]
	v_mfma_f32_16x16x32_bf16 v[16:19], v[68:71], v[188:191], v[16:19]
	v_mfma_f32_16x16x32_bf16 v[12:15], v[92:95], v[188:191], v[12:15]
	v_mfma_f32_16x16x32_bf16 v[64:67], v[80:83], v[168:171], v[64:67]
	v_mfma_f32_16x16x32_bf16 v[60:63], v[100:103], v[168:171], v[60:63]
	v_mfma_f32_16x16x32_bf16 v[48:51], v[80:83], v[176:179], v[48:51]
	v_mfma_f32_16x16x32_bf16 v[44:47], v[100:103], v[176:179], v[44:47]
	v_mfma_f32_16x16x32_bf16 v[32:35], v[80:83], v[184:187], v[32:35]
	v_mfma_f32_16x16x32_bf16 v[28:31], v[100:103], v[184:187], v[28:31]
	v_mfma_f32_16x16x32_bf16 v[16:19], v[80:83], v[208:211], v[16:19]
	v_mfma_f32_16x16x32_bf16 v[12:15], v[100:103], v[208:211], v[12:15]
	s_setprio 0
	s_setprio 1
	v_mfma_f32_16x16x32_bf16 v[56:59], v[112:115], v[156:159], v[56:59]
	v_mfma_f32_16x16x32_bf16 v[52:55], v[132:135], v[156:159], v[52:55]
	v_mfma_f32_16x16x32_bf16 v[40:43], v[112:115], v[172:175], v[40:43]
	v_mfma_f32_16x16x32_bf16 v[36:39], v[132:135], v[172:175], v[36:39]
	v_mfma_f32_16x16x32_bf16 v[24:27], v[112:115], v[180:183], v[24:27]
	v_mfma_f32_16x16x32_bf16 v[20:23], v[132:135], v[180:183], v[20:23]
	v_mfma_f32_16x16x32_bf16 v[8:11], v[112:115], v[188:191], v[8:11]
	v_mfma_f32_16x16x32_bf16 v[4:7], v[132:135], v[188:191], v[4:7]
	v_mfma_f32_16x16x32_bf16 v[56:59], v[120:123], v[168:171], v[56:59]
	v_mfma_f32_16x16x32_bf16 v[52:55], v[144:147], v[168:171], v[52:55]
	v_mfma_f32_16x16x32_bf16 v[40:43], v[120:123], v[176:179], v[40:43]
	v_mfma_f32_16x16x32_bf16 v[36:39], v[144:147], v[176:179], v[36:39]
	v_mfma_f32_16x16x32_bf16 v[24:27], v[120:123], v[184:187], v[24:27]
	v_mfma_f32_16x16x32_bf16 v[20:23], v[144:147], v[184:187], v[20:23]
	v_mfma_f32_16x16x32_bf16 v[8:11], v[120:123], v[208:211], v[8:11]
	v_mfma_f32_16x16x32_bf16 v[4:7], v[144:147], v[208:211], v[4:7]
	s_setprio 0
	s_barrier
	s_add_i32 s55, 0, 0x1c000
	v_add_u32_e32 v100, s54, v234
	v_add_u32_e32 v144, s55, v234
	ds_read_b128 v[68:71], v100
	ds_read_b128 v[80:83], v100 offset:1024
	ds_read_b128 v[92:95], v100 offset:2048
	ds_read_b128 v[100:103], v100 offset:3072
	ds_read_b128 v[112:115], v144
	ds_read_b128 v[120:123], v144 offset:1024
	ds_read_b128 v[132:135], v144 offset:2048
	ds_read_b128 v[144:147], v144 offset:3072
	s_add_u32 s26, s30, 0xb0000
	s_addc_u32 s27, s31, 0
	s_mov_b32 m0, s42
	v_lshl_add_u64 v[218:219], s[26:27], 0, v[0:1]
	ds_read_b128 v[156:159], v236 offset:32768
	ds_read_b128 v[168:171], v236 offset:33792
	ds_read_b128 v[172:175], v236 offset:34816
	ds_read_b128 v[176:179], v236 offset:35840
	ds_read_b128 v[180:183], v236 offset:36864
	ds_read_b128 v[184:187], v236 offset:37888
	ds_read_b128 v[188:191], v236 offset:38912
	ds_read_b128 v[208:211], v236 offset:39936
	global_load_lds_dwordx4 v[218:219], off
	s_mov_b32 m0, s43
	v_lshl_add_u64 v[218:219], s[26:27], 0, v[194:195]
	global_load_lds_dwordx4 v[218:219], off
	s_waitcnt vmcnt(8) lgkmcnt(0)
	s_barrier
	s_setprio 1
	v_mfma_f32_16x16x32_bf16 v[164:167], v[68:71], v[156:159], v[164:167]
	v_mfma_f32_16x16x32_bf16 v[160:163], v[92:95], v[156:159], v[160:163]
	v_mfma_f32_16x16x32_bf16 v[140:143], v[68:71], v[172:175], v[140:143]
	v_mfma_f32_16x16x32_bf16 v[136:139], v[92:95], v[172:175], v[136:139]
	v_mfma_f32_16x16x32_bf16 v[116:119], v[68:71], v[180:183], v[116:119]
	v_mfma_f32_16x16x32_bf16 v[108:111], v[92:95], v[180:183], v[108:111]
	v_mfma_f32_16x16x32_bf16 v[88:91], v[68:71], v[188:191], v[88:91]
	v_mfma_f32_16x16x32_bf16 v[84:87], v[92:95], v[188:191], v[84:87]
	v_mfma_f32_16x16x32_bf16 v[164:167], v[80:83], v[168:171], v[164:167]
	v_mfma_f32_16x16x32_bf16 v[160:163], v[100:103], v[168:171], v[160:163]
	v_mfma_f32_16x16x32_bf16 v[140:143], v[80:83], v[176:179], v[140:143]
	v_mfma_f32_16x16x32_bf16 v[136:139], v[100:103], v[176:179], v[136:139]
	v_mfma_f32_16x16x32_bf16 v[116:119], v[80:83], v[184:187], v[116:119]
	v_mfma_f32_16x16x32_bf16 v[108:111], v[100:103], v[184:187], v[108:111]
	v_mfma_f32_16x16x32_bf16 v[88:91], v[80:83], v[208:211], v[88:91]
	v_mfma_f32_16x16x32_bf16 v[84:87], v[100:103], v[208:211], v[84:87]
	s_setprio 0
	s_setprio 1
	v_mfma_f32_16x16x32_bf16 v[152:155], v[112:115], v[156:159], v[152:155]
	v_mfma_f32_16x16x32_bf16 v[148:151], v[132:135], v[156:159], v[148:151]
	v_mfma_f32_16x16x32_bf16 v[128:131], v[112:115], v[172:175], v[128:131]
	v_mfma_f32_16x16x32_bf16 v[124:127], v[132:135], v[172:175], v[124:127]
	v_mfma_f32_16x16x32_bf16 v[104:107], v[112:115], v[180:183], v[104:107]
	v_mfma_f32_16x16x32_bf16 v[96:99], v[132:135], v[180:183], v[96:99]
	v_mfma_f32_16x16x32_bf16 v[76:79], v[112:115], v[188:191], v[76:79]
	v_mfma_f32_16x16x32_bf16 v[72:75], v[132:135], v[188:191], v[72:75]
	v_mfma_f32_16x16x32_bf16 v[152:155], v[120:123], v[168:171], v[152:155]
	v_mfma_f32_16x16x32_bf16 v[148:151], v[144:147], v[168:171], v[148:151]
	v_mfma_f32_16x16x32_bf16 v[128:131], v[120:123], v[176:179], v[128:131]
	v_mfma_f32_16x16x32_bf16 v[124:127], v[144:147], v[176:179], v[124:127]
	v_mfma_f32_16x16x32_bf16 v[104:107], v[120:123], v[184:187], v[104:107]
	v_mfma_f32_16x16x32_bf16 v[96:99], v[144:147], v[184:187], v[96:99]
	v_mfma_f32_16x16x32_bf16 v[76:79], v[120:123], v[208:211], v[76:79]
	v_mfma_f32_16x16x32_bf16 v[72:75], v[144:147], v[208:211], v[72:75]
	s_setprio 0
	s_barrier
; #define PG8_STAGE(bufoff, gbase, voff) do { _Pragma("unroll") for (int _i = 0; _i < 2; ++_i) \
;         __builtin_amdgcn_global_load_lds((const unsigned*)((const char*)(gbase) + (voff)[_i]), (PG8_LAS unsigned*)(lds + (bufoff) + ldsw + _i * 8192), 16, 0, 0); } while (0)
; #define PG8_LDA(dst, b, h) do { _Pragma("unroll") for (int m = 0; m < 4; ++m) _Pragma("unroll") for (int k = 0; k < 2; ++k) dst[m][k] = *(const PG8_LAS bf16x8*)(lds + PG8_SA(b, h) + aoff + m * 2048 + k * 1024); } while (0)
; #define PG8_MMA(ai, bj, At, Bt) do { __builtin_amdgcn_s_setprio(1); _Pragma("unroll") for (int m = 0; m < 4; ++m) _Pragma("unroll") for (int n = 0; n < 2; ++n) _Pragma("unroll") for (int k = 0; k < 2; ++k) \
;         acc[ai][bj][m][n] = __builtin_amdgcn_mfma_f32_16x16x32_bf16(Bt[n][k], At[m][k], acc[ai][bj][m][n], 0, 0, 0); __builtin_amdgcn_s_setprio(0); } while (0)
; #define PG8_WAIT_V(n) asm volatile("s_waitcnt vmcnt(" #n ")" ::: "memory")
; #define PG8_WAIT_L(n) asm volatile("s_waitcnt lgkmcnt(" #n ")" ::: "memory")
; #define PG8_BAR __builtin_amdgcn_s_barrier()
; #define PG8_SCHED __builtin_amdgcn_sched_barrier(0)
; template <class Epi, class Sched, bool ALIGN_EPI = false, bool SP2 = false>
; __device__ __forceinline__ void gemm_phase(PG8_LAS unsigned char* lds, const Gemm g, const Sched& S, const Epi& E) {
;     ...
;             PG8_LDA(At, 1, 1); PG8_STAGE(PG8_SB(1, 0), b3, voffB); PG8_STAGE(PG8_SB(1, 1), b3 + hstep, voffB); PG8_STAGE(PG8_SA(1, 0), a3, voffA);
;             PG8_WAIT_V(8); PG8_WAIT_L(0); PG8_BAR; PG8_MMA(1, 0, At, B0); PG8_MMA(1, 1, At, B1); PG8_BAR; PG8_SCHED;
	s_add_i32 s26, s54, s39
	s_add_i32 m0, s26, 0xffffff80
	ds_read_b128 v[156:159], v236 offset:49152
	ds_read_b128 v[168:171], v236 offset:50176
	ds_read_b128 v[172:175], v236 offset:51200
	ds_read_b128 v[176:179], v236 offset:52224
	ds_read_b128 v[180:183], v236 offset:53248
	ds_read_b128 v[184:187], v236 offset:54272
	ds_read_b128 v[188:191], v236 offset:55296
	ds_read_b128 v[208:211], v236 offset:56320
	global_load_lds_dwordx4 v[198:199], off offset:128
	s_add_i32 m0, s26, 0x1f80
	s_add_u32 s26, s28, 0xb0080
	s_addc_u32 s27, s29, 0
	s_add_i32 s28, s55, s39
	global_load_lds_dwordx4 v[212:213], off offset:128
	s_mov_b32 m0, s28
	v_lshl_add_u64 v[198:199], s[26:27], 0, v[192:193]
	global_load_lds_dwordx4 v[198:199], off
	s_add_i32 m0, s28, 0x2000
	v_lshl_add_u64 v[198:199], s[26:27], 0, v[202:203]
	global_load_lds_dwordx4 v[198:199], off
	s_add_i32 m0, s47, 0xffffff80
	s_add_u32 s44, s44, 0x100
	s_addc_u32 s45, s45, 0
	global_load_lds_dwordx4 v[214:215], off offset:128
	s_add_i32 m0, s48, 0xffffff80
	s_mov_b64 s[26:27], s[8:9]
	global_load_lds_dwordx4 v[216:217], off offset:128
	s_waitcnt vmcnt(8) lgkmcnt(0)
	s_barrier
	s_setprio 1
	v_mfma_f32_16x16x32_bf16 v[64:67], v[68:71], v[156:159], v[64:67]
	v_mfma_f32_16x16x32_bf16 v[60:63], v[92:95], v[156:159], v[60:63]
	v_mfma_f32_16x16x32_bf16 v[48:51], v[68:71], v[172:175], v[48:51]
	v_mfma_f32_16x16x32_bf16 v[44:47], v[92:95], v[172:175], v[44:47]
	v_mfma_f32_16x16x32_bf16 v[32:35], v[68:71], v[180:183], v[32:35]
	v_mfma_f32_16x16x32_bf16 v[28:31], v[92:95], v[180:183], v[28:31]
	v_mfma_f32_16x16x32_bf16 v[16:19], v[68:71], v[188:191], v[16:19]
	v_mfma_f32_16x16x32_bf16 v[12:15], v[92:95], v[188:191], v[12:15]
	v_mfma_f32_16x16x32_bf16 v[64:67], v[80:83], v[168:171], v[64:67]
	v_mfma_f32_16x16x32_bf16 v[60:63], v[100:103], v[168:171], v[60:63]
	v_mfma_f32_16x16x32_bf16 v[48:51], v[80:83], v[176:179], v[48:51]
	v_mfma_f32_16x16x32_bf16 v[44:47], v[100:103], v[176:179], v[44:47]
	v_mfma_f32_16x16x32_bf16 v[32:35], v[80:83], v[184:187], v[32:35]
	v_mfma_f32_16x16x32_bf16 v[28:31], v[100:103], v[184:187], v[28:31]
	v_mfma_f32_16x16x32_bf16 v[16:19], v[80:83], v[208:211], v[16:19]
	v_mfma_f32_16x16x32_bf16 v[12:15], v[100:103], v[208:211], v[12:15]
	s_setprio 0
	s_setprio 1
	v_mfma_f32_16x16x32_bf16 v[56:59], v[112:115], v[156:159], v[56:59]
	v_mfma_f32_16x16x32_bf16 v[52:55], v[132:135], v[156:159], v[52:55]
	v_mfma_f32_16x16x32_bf16 v[40:43], v[112:115], v[172:175], v[40:43]
	v_mfma_f32_16x16x32_bf16 v[36:39], v[132:135], v[172:175], v[36:39]
	v_mfma_f32_16x16x32_bf16 v[24:27], v[112:115], v[180:183], v[24:27]
	v_mfma_f32_16x16x32_bf16 v[20:23], v[132:135], v[180:183], v[20:23]
	v_mfma_f32_16x16x32_bf16 v[8:11], v[112:115], v[188:191], v[8:11]
	v_mfma_f32_16x16x32_bf16 v[4:7], v[132:135], v[188:191], v[4:7]
	v_mfma_f32_16x16x32_bf16 v[56:59], v[120:123], v[168:171], v[56:59]
	v_mfma_f32_16x16x32_bf16 v[52:55], v[144:147], v[168:171], v[52:55]
	v_mfma_f32_16x16x32_bf16 v[40:43], v[120:123], v[176:179], v[40:43]
	v_mfma_f32_16x16x32_bf16 v[36:39], v[144:147], v[176:179], v[36:39]
	v_mfma_f32_16x16x32_bf16 v[24:27], v[120:123], v[184:187], v[24:27]
	v_mfma_f32_16x16x32_bf16 v[20:23], v[144:147], v[184:187], v[20:23]
	v_mfma_f32_16x16x32_bf16 v[8:11], v[120:123], v[208:211], v[8:11]
	v_mfma_f32_16x16x32_bf16 v[4:7], v[144:147], v[208:211], v[4:7]
	s_setprio 0
	s_barrier
	s_add_i32 s53, s53, 2
	s_cmp_gt_u32 s53, 41
	s_cbranch_scc0 .LBB0_480
	s_and_b64 vcc, exec, s[20:21]
	s_cbranch_vccz .LBB0_483
	s_barrier
